# filter-final h2 row loads all in flight (32 per 2 t-steps) with counted vmcnt; rowpass wave sums via DPP reduction instead of 6 ds_bpermute round trips
# speedup vs baseline: 1.0270x; 1.0095x over previous
; __device__ __forceinline__ void filt_final_item(const Params& p, int l, int Lsel, int o, int cb, char* smem) {
;     ...
;   for (int t = tl; t < L; t += 32) {
;     const float4* hr = (const float4*)(h2 + (size_t)t * 64);
;     float s = fb;
; #pragma unroll
;     for (int k4 = 0; k4 < 16; ++k4) {
;       const float4 hv = hr[k4];
;       s += hv.x * w[k4 * 4] + hv.y * w[k4 * 4 + 1] + hv.z * w[k4 * 4 + 2] + hv.w * w[k4 * 4 + 3];
;     }
;     const float val = s * expf(-((float)t / (float)L) * rate);
;     if (dir == 0) { G[L - t] = f2bf(val); asum += fabsf(val); }
;     else if (t >= 1) { G[L + t] = f2bf(val); asum += fabsf(val); }
.LBB0_178:
	v_lshl_add_u64 v[14:15], s[90:91], 0, v[12:13]
	v_add_co_u32_e32 v16, vcc, 0x3f31c000, v14
	s_mov_b64 s[18:19], 0x3f31c000
	s_nop 0
	v_addc_co_u32_e32 v17, vcc, 0, v15, vcc
	v_add_co_u32_e32 v118, vcc, 0x3f31e000, v14
	s_nop 1
	v_addc_co_u32_e32 v119, vcc, 0, v15, vcc
	global_load_dwordx4 v[90:93], v[16:17], off
	global_load_dwordx4 v[102:105], v[16:17], off offset:16
	global_load_dwordx4 v[98:101], v[16:17], off offset:32
	global_load_dwordx4 v[94:97], v[16:17], off offset:48
	global_load_dwordx4 v[106:109], v[16:17], off offset:64
	global_load_dwordx4 v[110:113], v[16:17], off offset:80
	global_load_dwordx4 v[114:117], v[16:17], off offset:96
	global_load_dwordx4 v[136:139], v[16:17], off offset:112
	global_load_dwordx4 v[140:143], v[16:17], off offset:128
	global_load_dwordx4 v[144:147], v[16:17], off offset:144
	global_load_dwordx4 v[148:151], v[16:17], off offset:160
	global_load_dwordx4 v[156:159], v[16:17], off offset:176
	global_load_dwordx4 v[160:163], v[16:17], off offset:192
	global_load_dwordx4 v[164:167], v[16:17], off offset:208
	global_load_dwordx4 v[168:171], v[16:17], off offset:224
	global_load_dwordx4 v[176:179], v[16:17], off offset:240
	global_load_dwordx4 v[180:183], v[118:119], off
	global_load_dwordx4 v[186:189], v[118:119], off offset:16
	global_load_dwordx4 v[190:193], v[118:119], off offset:32
	global_load_dwordx4 v[198:201], v[118:119], off offset:48
	global_load_dwordx4 v[202:205], v[118:119], off offset:64
	global_load_dwordx4 v[206:209], v[118:119], off offset:80
	global_load_dwordx4 v[210:213], v[118:119], off offset:96
	global_load_dwordx4 v[214:217], v[118:119], off offset:112
	global_load_dwordx4 v[218:221], v[118:119], off offset:128
	global_load_dwordx4 v[222:225], v[118:119], off offset:144
	global_load_dwordx4 v[226:229], v[118:119], off offset:160
	global_load_dwordx4 v[230:233], v[118:119], off offset:176
	global_load_dwordx4 v[234:237], v[118:119], off offset:192
	global_load_dwordx4 v[238:241], v[118:119], off offset:208
	global_load_dwordx4 v[242:245], v[118:119], off offset:224
	global_load_dwordx4 v[248:251], v[118:119], off offset:240
	s_mov_b64 s[18:19], 0x3f31c040
	s_mov_b64 s[18:19], 0x3f31c080
	s_waitcnt vmcnt(31)
	v_mul_f32_e32 v0, v78, v91
	v_fmac_f32_e32 v0, v22, v90
	v_fmac_f32_e32 v0, v79, v92
	s_waitcnt vmcnt(28)
	v_mul_f32_e32 v9, v82, v103
	v_fmac_f32_e32 v9, v81, v102
	v_fmac_f32_e32 v0, v80, v93
	v_fmac_f32_e32 v9, v23, v104
	v_add_f32_e32 v0, v21, v0
	v_fmac_f32_e32 v9, v24, v105
	v_add_f32_e32 v0, v0, v9
	v_mul_f32_e32 v9, v26, v99
	v_fmac_f32_e32 v9, v25, v98
	v_fmac_f32_e32 v9, v27, v100
	v_fmac_f32_e32 v9, v28, v101
	v_add_f32_e32 v0, v0, v9
	v_mul_f32_e32 v9, v30, v95
	v_fmac_f32_e32 v9, v29, v94
	v_fmac_f32_e32 v9, v31, v96
	v_fmac_f32_e32 v9, v32, v97
	v_add_f32_e32 v0, v0, v9
	s_mov_b64 s[18:19], 0x3f31c0c0
	s_waitcnt vmcnt(27)
	v_mul_f32_e32 v9, v34, v107
	v_fmac_f32_e32 v9, v33, v106
	v_fmac_f32_e32 v9, v35, v108
	v_fmac_f32_e32 v9, v36, v109
	v_add_f32_e32 v0, v0, v9
	s_waitcnt vmcnt(24)
	v_mul_f32_e32 v9, v38, v111
	v_fmac_f32_e32 v9, v37, v110
	v_fmac_f32_e32 v9, v39, v112
	v_fmac_f32_e32 v9, v40, v113
	v_add_f32_e32 v0, v0, v9
	v_mul_f32_e32 v9, v42, v115
	v_fmac_f32_e32 v9, v41, v114
	v_fmac_f32_e32 v9, v43, v116
	v_fmac_f32_e32 v9, v44, v117
	v_add_f32_e32 v0, v0, v9
	v_mul_f32_e32 v9, v46, v137
	v_fmac_f32_e32 v9, v45, v136
	v_fmac_f32_e32 v9, v47, v138
	v_fmac_f32_e32 v9, v48, v139
	v_add_f32_e32 v0, v0, v9
	s_waitcnt vmcnt(23)
	v_mul_f32_e32 v9, v50, v141
	v_fmac_f32_e32 v9, v49, v140
	v_fmac_f32_e32 v9, v51, v142
	v_fmac_f32_e32 v9, v52, v143
	v_add_f32_e32 v0, v0, v9
	s_waitcnt vmcnt(20)
	v_mul_f32_e32 v9, v54, v145
	v_fmac_f32_e32 v9, v53, v144
	v_fmac_f32_e32 v9, v55, v146
	v_fmac_f32_e32 v9, v56, v147
	v_add_f32_e32 v0, v0, v9
	v_mul_f32_e32 v9, v58, v149
	v_fmac_f32_e32 v9, v57, v148
	v_fmac_f32_e32 v9, v59, v150
	v_fmac_f32_e32 v9, v60, v151
	v_add_f32_e32 v0, v0, v9
	v_mul_f32_e32 v9, v62, v157
	v_fmac_f32_e32 v9, v61, v156
	v_fmac_f32_e32 v9, v63, v158
	v_fmac_f32_e32 v9, v64, v159
	s_nop 0
	s_nop 0
	v_add_f32_e32 v0, v0, v9
	s_waitcnt vmcnt(19)
	v_mul_f32_e32 v9, v66, v161
	v_fmac_f32_e32 v9, v65, v160
	v_fmac_f32_e32 v9, v67, v162
	v_fmac_f32_e32 v9, v68, v163
	v_add_f32_e32 v0, v0, v9
	s_waitcnt vmcnt(16)
	v_mul_f32_e32 v9, v70, v165
	v_fmac_f32_e32 v9, v69, v164
	v_fmac_f32_e32 v9, v71, v166
	v_fmac_f32_e32 v9, v72, v167
	v_add_f32_e32 v0, v0, v9
	v_mul_f32_e32 v9, v74, v169
	v_fmac_f32_e32 v9, v73, v168
	v_fmac_f32_e32 v9, v75, v170
	v_fmac_f32_e32 v9, v76, v171
	v_add_f32_e32 v0, v0, v9
	v_mul_f32_e32 v9, v83, v177
	v_fmac_f32_e32 v9, v77, v176
	v_fmac_f32_e32 v9, v84, v178
	v_fmac_f32_e32 v9, v85, v179
	v_add_f32_e32 v0, v0, v9
	v_cvt_f32_i32_e32 v9, v8
	v_div_scale_f32 v16, s[18:19], v87, v87, -v9
	v_rcp_f32_e32 v17, v16
	s_nop 0
	v_fma_f32 v18, -v16, v17, 1.0
	v_fmac_f32_e32 v17, v18, v17
	v_div_scale_f32 v18, vcc, -v9, v87, -v9
	v_mul_f32_e32 v19, v18, v17
	v_fma_f32 v89, -v16, v19, v18
	v_fmac_f32_e32 v19, v89, v17
	v_fma_f32 v16, -v16, v19, v18
	v_div_fmas_f32 v16, v16, v17, v19
	v_div_fixup_f32 v9, v16, v87, -v9
	v_mul_f32_e32 v9, v86, v9
	v_mul_f32_e32 v16, 0x3fb8aa3b, v9
	v_fma_f32 v17, v9, s27, -v16
	v_rndne_f32_e32 v18, v16
	v_fmac_f32_e32 v17, 0x32a5705f, v9
	v_sub_f32_e32 v16, v16, v18
	v_add_f32_e32 v16, v16, v17
	v_exp_f32_e32 v16, v16
	v_cvt_i32_f32_e32 v17, v18
	v_cmp_ngt_f32_e32 vcc, s28, v9
	v_ldexp_f32 v16, v16, v17
	s_nop 0
	v_cndmask_b32_e32 v16, 0, v16, vcc
	v_cmp_nlt_f32_e32 vcc, s29, v9
	s_nop 1
	v_cndmask_b32_e32 v9, v20, v16, vcc
	v_mul_f32_e32 v9, v9, v0
	s_and_saveexec_b64 s[18:19], s[0:1]
	s_xor_b64 s[18:19], exec, s[18:19]
	s_cbranch_execz .LBB0_182
	v_cmp_lt_i32_e32 vcc, 0, v8
	s_and_saveexec_b64 s[20:21], vcc
	s_cbranch_execz .LBB0_181
	v_add_u32_e32 v0, s36, v8
	v_cvt_pk_bf16_f32 v18, v9, s0
	v_lshl_add_u64 v[16:17], v[0:1], 1, v[4:5]
	v_add_f32_e64 v88, v88, |v9|
	global_store_short v[16:17], v18, off

; __device__ __forceinline__ void filt_final_item(const Params& p, int l, int Lsel, int o, int cb, char* smem) {
;     ...
;   for (int t = tl; t < L; t += 32) {
;     const float4* hr = (const float4*)(h2 + (size_t)t * 64);
;     float s = fb;
; #pragma unroll
;     for (int k4 = 0; k4 < 16; ++k4) {
;       const float4 hv = hr[k4];
;       s += hv.x * w[k4 * 4] + hv.y * w[k4 * 4 + 1] + hv.z * w[k4 * 4 + 2] + hv.w * w[k4 * 4 + 3];
;     }
;     const float val = s * expf(-((float)t / (float)L) * rate);
;     if (dir == 0) { G[L - t] = f2bf(val); asum += fabsf(val); }
;     else if (t >= 1) { G[L + t] = f2bf(val); asum += fabsf(val); }
.LBB0_184:
	s_or_b64 exec, exec, s[18:19]
	s_mov_b64 s[18:19], 0x3f31e000
	s_nop 0
	s_nop 0
	s_mov_b64 s[18:19], 0x3f31e040
	v_add_u32_e32 v0, 32, v8
	v_cvt_f32_i32_e32 v0, v0
	s_waitcnt vmcnt(15)
	v_mul_f32_e32 v9, v78, v181
	v_fmac_f32_e32 v9, v22, v180
	v_fmac_f32_e32 v9, v79, v182
	s_waitcnt vmcnt(12)
	v_mul_f32_e32 v89, v82, v187
	v_fmac_f32_e32 v89, v81, v186
	v_fmac_f32_e32 v9, v80, v183
	v_fmac_f32_e32 v89, v23, v188
	v_add_f32_e32 v9, v21, v9
	v_fmac_f32_e32 v89, v24, v189
	v_add_f32_e32 v9, v9, v89
	v_mul_f32_e32 v89, v26, v191
	v_fmac_f32_e32 v89, v25, v190
	v_fmac_f32_e32 v89, v27, v192
	v_fmac_f32_e32 v89, v28, v193
	v_add_f32_e32 v9, v9, v89
	v_mul_f32_e32 v89, v30, v199
	v_fmac_f32_e32 v89, v29, v198
	v_fmac_f32_e32 v89, v31, v200
	v_fmac_f32_e32 v89, v32, v201
	s_nop 0
	v_add_f32_e32 v9, v9, v89
	s_mov_b64 s[18:19], 0x3f31e080
	s_waitcnt vmcnt(11)
	v_mul_f32_e32 v89, v34, v203
	v_fmac_f32_e32 v89, v33, v202
	v_fmac_f32_e32 v89, v35, v204
	v_fmac_f32_e32 v89, v36, v205
	v_add_f32_e32 v9, v9, v89
	s_waitcnt vmcnt(8)
	v_mul_f32_e32 v89, v38, v207
	v_fmac_f32_e32 v89, v37, v206
	v_fmac_f32_e32 v89, v39, v208
	v_fmac_f32_e32 v89, v40, v209
	v_add_f32_e32 v9, v9, v89
	v_mul_f32_e32 v89, v42, v211
	v_fmac_f32_e32 v89, v41, v210
	v_fmac_f32_e32 v89, v43, v212
	v_fmac_f32_e32 v89, v44, v213
	v_add_f32_e32 v9, v9, v89
	v_mul_f32_e32 v89, v46, v215
	v_fmac_f32_e32 v89, v45, v214
	v_fmac_f32_e32 v89, v47, v216
	v_fmac_f32_e32 v89, v48, v217
	s_nop 0
	v_add_f32_e32 v9, v9, v89
	v_lshl_add_u64 v[14:15], v[14:15], 0, s[4:5]
	s_waitcnt vmcnt(7)
	v_mul_f32_e32 v89, v50, v219
	v_fmac_f32_e32 v89, v49, v218
	v_fmac_f32_e32 v89, v51, v220
	v_fmac_f32_e32 v89, v52, v221
	v_add_f32_e32 v9, v9, v89
	s_waitcnt vmcnt(4)
	v_mul_f32_e32 v89, v54, v223
	v_fmac_f32_e32 v89, v53, v222
	v_fmac_f32_e32 v89, v55, v224
	v_fmac_f32_e32 v89, v56, v225
	v_add_f32_e32 v9, v9, v89
	v_mul_f32_e32 v89, v58, v227
	v_fmac_f32_e32 v89, v57, v226
	v_fmac_f32_e32 v89, v59, v228
	v_fmac_f32_e32 v89, v60, v229
	v_add_f32_e32 v9, v9, v89
	v_mul_f32_e32 v89, v62, v231
	v_fmac_f32_e32 v89, v61, v230
	v_fmac_f32_e32 v89, v63, v232
	v_fmac_f32_e32 v89, v64, v233
	v_add_f32_e32 v9, v9, v89
	s_waitcnt vmcnt(3)
	v_mul_f32_e32 v14, v66, v235
	v_fmac_f32_e32 v14, v65, v234
	v_fmac_f32_e32 v14, v67, v236
	v_fmac_f32_e32 v14, v68, v237
	v_add_f32_e32 v9, v9, v14
	s_waitcnt vmcnt(0)
	v_mul_f32_e32 v14, v70, v239
	v_fmac_f32_e32 v14, v69, v238
	v_fmac_f32_e32 v14, v71, v240
	v_fmac_f32_e32 v14, v72, v241
	v_add_f32_e32 v9, v9, v14
	v_mul_f32_e32 v14, v74, v243
	v_fmac_f32_e32 v14, v73, v242
	v_fmac_f32_e32 v14, v75, v244
	v_fmac_f32_e32 v14, v76, v245
	v_add_f32_e32 v9, v9, v14
	v_mul_f32_e32 v14, v83, v249
	v_fmac_f32_e32 v14, v77, v248
	v_fmac_f32_e32 v14, v84, v250
	v_fmac_f32_e32 v14, v85, v251
	v_add_f32_e32 v9, v9, v14
	v_div_scale_f32 v14, s[18:19], v87, v87, -v0
	v_rcp_f32_e32 v15, v14
	s_nop 0
	v_fma_f32 v18, -v14, v15, 1.0
	v_fmac_f32_e32 v15, v18, v15
	v_div_scale_f32 v18, vcc, -v0, v87, -v0
	v_mul_f32_e32 v19, v18, v15
	v_fma_f32 v89, -v14, v19, v18
	v_fmac_f32_e32 v19, v89, v15
	v_fma_f32 v14, -v14, v19, v18
	v_div_fmas_f32 v14, v14, v15, v19
	v_div_fixup_f32 v0, v14, v87, -v0
	v_mul_f32_e32 v0, v86, v0
	v_mul_f32_e32 v14, 0x3fb8aa3b, v0
	v_fma_f32 v15, v0, s27, -v14
	v_rndne_f32_e32 v18, v14
	v_fmac_f32_e32 v15, 0x32a5705f, v0
	v_sub_f32_e32 v14, v14, v18
	v_add_f32_e32 v14, v14, v15
	v_exp_f32_e32 v14, v14
	v_cvt_i32_f32_e32 v15, v18
	v_cmp_ngt_f32_e32 vcc, s28, v0
	v_ldexp_f32 v14, v14, v15
	s_nop 0
	v_cndmask_b32_e32 v14, 0, v14, vcc
	v_cmp_nlt_f32_e32 vcc, s29, v0
	s_nop 1
	v_cndmask_b32_e32 v0, v20, v14, vcc
	v_mul_f32_e32 v9, v0, v9
	s_and_saveexec_b64 s[18:19], s[0:1]
	s_xor_b64 s[18:19], exec, s[18:19]
	s_cbranch_execz .LBB0_188
	v_cmp_lt_i32_e32 vcc, s30, v8
	s_and_saveexec_b64 s[20:21], vcc
	s_cbranch_execz .LBB0_187
	v_add3_u32 v0, s36, v8, 32
	v_cvt_pk_bf16_f32 v16, v9, s0
	v_lshl_add_u64 v[14:15], v[0:1], 1, v[4:5]
	v_add_f32_e64 v88, v88, |v9|
	global_store_short v[14:15], v16, off

; DI unsigned pack2(float lo, float hi) { f2v_ f = {lo, hi}; b2v_ b = __builtin_convertvector(f, b2v_); return __builtin_bit_cast(unsigned, b); }
; __device__ __forceinline__ void rowpass(const Params& p, int mode, const float* __restrict__ lg, const float* __restrict__ lb,
;                         const float* __restrict__ modl, int shoff, int scoff) {
;     ...
;   for (int row = blockIdx.x * NW + wave; row < R; row += gridDim.x * NW) {
;     const int b = row / NTOK, n = row % NTOK;
;     const int mi = n < CTXL ? 16 : b;
;     float4 v[4];
;     bft* xr = Xs + (size_t)row * D;
;     if (mode & 8) {
;       const float* src = (n < CTXL) ? p.in[I_CTX] + ((size_t)b * CTXL + n) * D : p.in[I_X] + ((size_t)b * SEQ + (n - CTXL)) * D;
; #pragma unroll
;       for (int k = 0; k < 4; ++k) v[k] = *(const float4*)(src + CK(k));
; #pragma unroll
;       for (int i = 0; i < 2; ++i) {
;         u32x4 w;
;         w.x = pack2(v[2 * i].x, v[2 * i].y); w.y = pack2(v[2 * i].z, v[2 * i].w);
;         w.z = pack2(v[2 * i + 1].x, v[2 * i + 1].y); w.w = pack2(v[2 * i + 1].z, v[2 * i + 1].w);
;         *(u32x4*)(xr + i * 512 + lane * 8) = w;
;       }
;     ...
;     if (mode & 4) {
;       float s = 0.f;
; #pragma unroll
;       for (int i = 0; i < 4; ++i) s += v[i].x + v[i].y + v[i].z + v[i].w;
;       const float mu = wave_sum(s) * (1.f / D);
.LBB0_198:
	v_mul_hi_i32 v12, v0, s3
	v_lshrrev_b32_e32 v13, 31, v12
	v_ashrrev_i32_e32 v12, 11, v12
	v_ashrrev_i32_e32 v1, 31, v0
	s_waitcnt vmcnt(57)
	v_add_u32_e32 v28, v12, v13
	v_lshlrev_b64 v[26:27], 11, v[0:1]
	v_mul_i32_i24_e32 v1, 0x1100, v28
	v_sub_u32_e32 v1, v0, v1
	v_cmp_gt_i32_e32 vcc, s10, v1
	s_waitcnt vmcnt(55)
	v_add_u32_e32 v30, 0xffffff00, v1
	v_ashrrev_i32_e32 v29, 31, v28
	s_waitcnt vmcnt(54)
	v_ashrrev_i32_e32 v31, 31, v1
	v_cndmask_b32_e32 v30, v30, v1, vcc
	v_cndmask_b32_e64 v1, 24, 20, vcc
	v_lshl_add_u64 v[12:13], v[8:9], 0, v[26:27]
	s_waitcnt vmcnt(10)
	v_lshl_add_u64 v[74:75], v[4:5], 0, v[26:27]
	v_cndmask_b32_e64 v25, v28, 16, vcc
	v_cndmask_b32_e32 v27, v20, v21, vcc
	v_cndmask_b32_e32 v26, v22, v23, vcc
	v_cndmask_b32_e32 v31, 0, v31, vcc
	v_lshlrev_b64 v[28:29], v1, v[28:29]
	v_mul_hi_i32_i24_e32 v33, 0x6000, v25
	v_mul_i32_i24_e32 v32, 0x6000, v25
	v_lshlrev_b64 v[30:31], 12, v[30:31]
	v_lshl_add_u64 v[26:27], v[26:27], 0, v[28:29]
	v_lshl_add_u64 v[32:33], s[96:97], 0, v[32:33]
	v_lshl_add_u64 v[26:27], v[26:27], 0, v[30:31]
	v_lshl_add_u64 v[28:29], v[32:33], 0, s[8:9]
	v_lshl_add_u64 v[38:39], v[26:27], 0, v[2:3]
	v_lshl_add_u64 v[62:63], v[32:33], 0, v[2:3]
	v_lshl_add_u64 v[70:71], v[28:29], 0, v[2:3]
	v_lshl_add_u64 v[54:55], v[28:29], 0, v[10:11]
	global_load_dwordx4 v[26:29], v[38:39], off
	global_load_dwordx4 v[30:33], v[38:39], off offset:16
	global_load_dwordx4 v[34:37], v[38:39], off offset:2048
	s_nop 0
	global_load_dwordx4 v[38:41], v[38:39], off offset:2064
	v_add_u32_e32 v0, s2, v0
	v_cmp_lt_i32_e64 s[0:1], s12, v0
	s_or_b64 s[6:7], s[0:1], s[6:7]
	s_waitcnt vmcnt(3)
	v_cvt_pk_bf16_f32 v42, v26, v27
	v_cvt_pk_bf16_f32 v43, v28, v29
	s_waitcnt vmcnt(2)
	v_cvt_pk_bf16_f32 v44, v30, v31
	v_cvt_pk_bf16_f32 v45, v32, v33
	v_mov_b32_e32 v50, v26
	v_mov_b32_e32 v51, v30
	v_mov_b32_e32 v52, v27
	v_mov_b32_e32 v53, v31
	s_waitcnt vmcnt(1)
	v_cvt_pk_bf16_f32 v46, v34, v35
	v_cvt_pk_bf16_f32 v47, v36, v37
	s_waitcnt vmcnt(0)
	v_cvt_pk_bf16_f32 v48, v38, v39
	v_cvt_pk_bf16_f32 v49, v40, v41
	v_mov_b32_e32 v56, v28
	v_mov_b32_e32 v57, v32
	global_store_dwordx4 v[12:13], v[42:45], off
	global_store_dwordx4 v[12:13], v[46:49], off offset:1024
	v_pk_add_f32 v[12:13], v[50:51], v[52:53]
	v_mov_b32_e32 v76, v29
	v_mov_b32_e32 v77, v33
	v_mov_b32_e32 v58, v34
	v_mov_b32_e32 v59, v38
	v_mov_b32_e32 v60, v35
	v_mov_b32_e32 v61, v39
	v_pk_add_f32 v[12:13], v[12:13], v[56:57]
	v_mov_b32_e32 v64, v36
	v_mov_b32_e32 v65, v40
	v_pk_add_f32 v[42:43], v[58:59], v[60:61]
	v_pk_add_f32 v[12:13], v[12:13], v[76:77]
	v_mov_b32_e32 v78, v37
	v_mov_b32_e32 v79, v41
	v_pk_add_f32 v[80:81], v[42:43], v[64:65]
	v_add_f32_e32 v1, 0, v12
	v_pk_add_f32 v[76:77], v[80:81], v[78:79]
	v_add_f32_e32 v1, v1, v13
	v_add_f32_e32 v1, v1, v76
	v_add_f32_e32 v1, v1, v77
	global_load_dwordx4 v[42:45], v[62:63], off offset:2064
	global_load_dwordx4 v[46:49], v[62:63], off offset:2048
	global_load_dwordx4 v[50:53], v[54:55], off offset:16
	s_nop 0
	global_load_dwordx4 v[54:57], v[54:55], off
	s_nop 0
	global_load_dwordx4 v[58:61], v[62:63], off offset:16
	s_nop 0
	global_load_dwordx4 v[62:65], v[62:63], off
	s_nop 0
	global_load_dwordx4 v[66:69], v[70:71], off offset:16
	s_nop 0
	global_load_dwordx4 v[70:73], v[70:71], off
	s_waitcnt lgkmcnt(0)
; DI unsigned pack2(float lo, float hi) { f2v_ f = {lo, hi}; b2v_ b = __builtin_convertvector(f, b2v_); return __builtin_bit_cast(unsigned, b); }
; __device__ __forceinline__ void rowpass(const Params& p, int mode, const float* __restrict__ lg, const float* __restrict__ lb,
;                         const float* __restrict__ modl, int shoff, int scoff) {
;     ...
;       const float mu = wave_sum(s) * (1.f / D);
;       float q = 0.f;
; #pragma unroll
;       for (int i = 0; i < 4; ++i) {
;         v[i].x -= mu; v[i].y -= mu; v[i].z -= mu; v[i].w -= mu;
;         q += v[i].x * v[i].x + v[i].y * v[i].y + v[i].z * v[i].z + v[i].w * v[i].w;
;       }
;       const float rstd = rsqrtf(wave_sum(q) * (1.f / D) + LN_EPS);
;       const float* mr = modl + (size_t)mi * 6144;
;       unsigned ow[8];
; #pragma unroll
;       for (int k = 0; k < 4; ++k) {
;         const int c = CK(k);
;         const float4 sh = *(const float4*)(mr + shoff + c), sc = *(const float4*)(mr + scoff + c);
;         ow[2 * k] = pack2(v[k].x * rstd * (1.f + sc.x) + sh.x, v[k].y * rstd * (1.f + sc.y) + sh.y);
;         ow[2 * k + 1] = pack2(v[k].z * rstd * (1.f + sc.z) + sh.z, v[k].w * rstd * (1.f + sc.w) + sh.w);
;       }
; #pragma unroll
;       for (int i = 0; i < 2; ++i) {
;         const u32x4 w = {ow[4 * i], ow[4 * i + 1], ow[4 * i + 2], ow[4 * i + 3]};
;         *(u32x4*)(XN + (size_t)row * D + i * 512 + lane * 8) = w;
;       }
	s_nop 1
	v_add_f32_dpp v1, v1, v1 quad_perm:[1,0,3,2] row_mask:0xf bank_mask:0xf
	s_nop 1
	v_add_f32_dpp v1, v1, v1 quad_perm:[2,3,0,1] row_mask:0xf bank_mask:0xf
	s_nop 1
	v_add_f32_dpp v1, v1, v1 row_half_mirror row_mask:0xf bank_mask:0xf
	s_nop 1
	v_add_f32_dpp v1, v1, v1 row_mirror row_mask:0xf bank_mask:0xf
	s_nop 1
	v_add_f32_dpp v1, v1, v1 row_bcast:15 row_mask:0xa bank_mask:0xf
	s_nop 1
	v_add_f32_dpp v1, v1, v1 row_bcast:31 row_mask:0xc bank_mask:0xf
	s_nop 1
	v_readlane_b32 s98, v1, 63
	s_nop 1
	v_mov_b32_e32 v1, s98
	v_mul_f32_e32 v12, 0x3a800000, v1
	v_pk_add_f32 v[40:41], v[40:41], v[12:13] op_sel_hi:[1,0] neg_lo:[0,1] neg_hi:[0,1]
	v_pk_add_f32 v[38:39], v[38:39], v[12:13] op_sel_hi:[1,0] neg_lo:[0,1] neg_hi:[0,1]
	v_pk_add_f32 v[36:37], v[36:37], v[12:13] op_sel_hi:[1,0] neg_lo:[0,1] neg_hi:[0,1]
	v_pk_add_f32 v[34:35], v[34:35], v[12:13] op_sel_hi:[1,0] neg_lo:[0,1] neg_hi:[0,1]
	v_pk_add_f32 v[32:33], v[32:33], v[12:13] op_sel_hi:[1,0] neg_lo:[0,1] neg_hi:[0,1]
	v_pk_add_f32 v[30:31], v[30:31], v[12:13] op_sel_hi:[1,0] neg_lo:[0,1] neg_hi:[0,1]
	v_pk_add_f32 v[28:29], v[28:29], v[12:13] op_sel_hi:[1,0] neg_lo:[0,1] neg_hi:[0,1]
	v_pk_add_f32 v[12:13], v[26:27], v[12:13] op_sel_hi:[1,0] neg_lo:[0,1] neg_hi:[0,1]
	v_mov_b32_e32 v80, v39
	v_mov_b32_e32 v81, v35
	v_mov_b32_e32 v88, v13
	v_mov_b32_e32 v89, v31
	v_mov_b32_e32 v78, v38
	v_mov_b32_e32 v79, v34
	v_mov_b32_e32 v86, v12
	v_mov_b32_e32 v87, v30
	v_pk_mul_f32 v[80:81], v[80:81], v[80:81]
	v_pk_mul_f32 v[88:89], v[88:89], v[88:89]
	v_mov_b32_e32 v26, v40
	v_mov_b32_e32 v27, v36
	v_mov_b32_e32 v82, v28
	v_mov_b32_e32 v83, v32
	v_pk_fma_f32 v[78:79], v[78:79], v[78:79], v[80:81]
	v_pk_fma_f32 v[80:81], v[86:87], v[86:87], v[88:89]
	v_mov_b32_e32 v76, v41
	v_mov_b32_e32 v77, v37
	v_mov_b32_e32 v84, v29
	v_mov_b32_e32 v85, v33
	v_pk_fma_f32 v[26:27], v[26:27], v[26:27], v[78:79]
	v_pk_fma_f32 v[78:79], v[82:83], v[82:83], v[80:81]
	v_pk_fma_f32 v[26:27], v[76:77], v[76:77], v[26:27]
	v_pk_fma_f32 v[76:77], v[84:85], v[84:85], v[78:79]
	s_waitcnt vmcnt(5)
	v_pk_add_f32 v[52:53], v[52:53], 1.0 op_sel_hi:[1,0]
	v_add_f32_e32 v1, v76, v77
	v_add_f32_e32 v1, v27, v1
	v_add_f32_e32 v1, v26, v1
	v_pk_add_f32 v[26:27], v[50:51], 1.0 op_sel_hi:[1,0]
	s_waitcnt vmcnt(4)
	v_pk_add_f32 v[50:51], v[56:57], 1.0 op_sel_hi:[1,0]
	s_waitcnt vmcnt(1)
	v_pk_add_f32 v[56:57], v[68:69], 1.0 op_sel_hi:[1,0]
	s_waitcnt vmcnt(0)
	v_pk_add_f32 v[68:69], v[72:73], 1.0 op_sel_hi:[1,0]
	v_pk_add_f32 v[66:67], v[66:67], 1.0 op_sel_hi:[1,0]
	v_pk_add_f32 v[70:71], v[70:71], 1.0 op_sel_hi:[1,0]
	v_pk_add_f32 v[54:55], v[54:55], 1.0 op_sel_hi:[1,0]
	s_waitcnt lgkmcnt(0)
	s_nop 1
	v_add_f32_dpp v1, v1, v1 quad_perm:[1,0,3,2] row_mask:0xf bank_mask:0xf
	s_nop 1
	v_add_f32_dpp v1, v1, v1 quad_perm:[2,3,0,1] row_mask:0xf bank_mask:0xf
	s_nop 1
	v_add_f32_dpp v1, v1, v1 row_half_mirror row_mask:0xf bank_mask:0xf
	s_nop 1
	v_add_f32_dpp v1, v1, v1 row_mirror row_mask:0xf bank_mask:0xf
	s_nop 1
	v_add_f32_dpp v1, v1, v1 row_bcast:15 row_mask:0xa bank_mask:0xf
	s_nop 1
	v_add_f32_dpp v1, v1, v1 row_bcast:31 row_mask:0xc bank_mask:0xf
	s_nop 1
	v_readlane_b32 s98, v1, 63
	s_nop 1
	v_mov_b32_e32 v1, s98
	v_fmamk_f32 v1, v1, 0x3a800000, v24
	v_mul_f32_e32 v25, 0x4b800000, v1
	v_cmp_gt_f32_e32 vcc, s11, v1
	s_nop 1
	v_cndmask_b32_e32 v1, v1, v25, vcc
	v_rsq_f32_e32 v1, v1
	s_nop 0
	v_mul_f32_e32 v25, 0x45800000, v1
	v_cndmask_b32_e32 v72, v1, v25, vcc
	v_pk_mul_f32 v[12:13], v[12:13], v[72:73] op_sel_hi:[1,0]
	v_pk_mul_f32 v[28:29], v[28:29], v[72:73] op_sel_hi:[1,0]
	v_pk_mul_f32 v[30:31], v[30:31], v[72:73] op_sel_hi:[1,0]
	v_pk_mul_f32 v[32:33], v[32:33], v[72:73] op_sel_hi:[1,0]
	v_pk_mul_f32 v[34:35], v[34:35], v[72:73] op_sel_hi:[1,0]
	v_pk_mul_f32 v[36:37], v[36:37], v[72:73] op_sel_hi:[1,0]
	v_pk_mul_f32 v[38:39], v[38:39], v[72:73] op_sel_hi:[1,0]
	v_pk_mul_f32 v[40:41], v[40:41], v[72:73] op_sel_hi:[1,0]
	v_pk_fma_f32 v[12:13], v[70:71], v[12:13], v[62:63]
	v_pk_fma_f32 v[28:29], v[68:69], v[28:29], v[64:65]
	v_pk_fma_f32 v[30:31], v[66:67], v[30:31], v[58:59]
	v_pk_fma_f32 v[32:33], v[56:57], v[32:33], v[60:61]
	v_pk_fma_f32 v[34:35], v[34:35], v[54:55], v[46:47]
	v_pk_fma_f32 v[36:37], v[36:37], v[50:51], v[48:49]
	v_pk_fma_f32 v[38:39], v[38:39], v[26:27], v[42:43]
	v_pk_fma_f32 v[40:41], v[40:41], v[52:53], v[44:45]
	v_cvt_pk_bf16_f32 v26, v12, v13
	v_cvt_pk_bf16_f32 v27, v28, v29
	v_cvt_pk_bf16_f32 v28, v30, v31
	v_cvt_pk_bf16_f32 v29, v32, v33
	v_cvt_pk_bf16_f32 v30, v34, v35
	v_cvt_pk_bf16_f32 v31, v36, v37
	v_cvt_pk_bf16_f32 v32, v38, v39
	v_cvt_pk_bf16_f32 v33, v40, v41
	global_store_dwordx4 v[74:75], v[26:29], off
	global_store_dwordx4 v[74:75], v[30:33], off offset:1024
	s_andn2_b64 exec, exec, s[6:7]
	s_cbranch_execnz .LBB0_198

; __device__ __forceinline__ void rowpass(const Params& p, int mode, const float* __restrict__ lg, const float* __restrict__ lb,
;                         const float* __restrict__ modl, int shoff, int scoff) {
;     ...
; #pragma unroll
;       for (int i = 0; i < 2; ++i) {
;         const u32x4 w = *(const u32x4*)(xr + i * 512 + lane * 8);
;         v[2 * i].x = __uint_as_float(w.x << 16); v[2 * i].y = __uint_as_float(w.x & 0xffff0000u);
;         v[2 * i].z = __uint_as_float(w.y << 16); v[2 * i].w = __uint_as_float(w.y & 0xffff0000u);
;         v[2 * i + 1].x = __uint_as_float(w.z << 16); v[2 * i + 1].y = __uint_as_float(w.z & 0xffff0000u);
;         v[2 * i + 1].z = __uint_as_float(w.w << 16); v[2 * i + 1].w = __uint_as_float(w.w & 0xffff0000u);
;       }
;     }
;     if (mode & 1) {
;       float s = 0.f;
; #pragma unroll
;       for (int i = 0; i < 4; ++i) s += v[i].x + v[i].y + v[i].z + v[i].w;
;       const float mu = wave_sum(s) * (1.f / D);
;       float q = 0.f;
; #pragma unroll
;       for (int i = 0; i < 4; ++i) {
;         v[i].x -= mu; v[i].y -= mu; v[i].z -= mu; v[i].w -= mu;
;         q += v[i].x * v[i].x + v[i].y * v[i].y + v[i].z * v[i].z + v[i].w * v[i].w;
;       }
;       const float rstd = rsqrtf(wave_sum(q) * (1.f / D) + LN_EPS);
.LBB0_1302:
	v_mul_hi_i32 v32, v40, s17
	v_lshrrev_b32_e32 v33, 31, v32
	v_ashrrev_i32_e32 v32, 11, v32
	v_add_u32_e32 v32, v32, v33
	v_mul_i32_i24_e32 v33, 0x1100, v32
	v_ashrrev_i32_e32 v41, 31, v40
	v_sub_u32_e32 v33, v40, v33
	v_lshlrev_b64 v[48:49], 11, v[40:41]
	v_cmp_lt_i32_e32 vcc, s2, v33
	v_lshl_add_u64 v[64:65], v[44:45], 0, v[48:49]
	s_mov_b64 s[14:15], 0x4000
	v_cndmask_b32_e32 v47, 16, v32, vcc
	global_load_dwordx4 v[32:35], v[64:65], off
	global_load_dwordx4 v[36:39], v[64:65], off offset:1024
	v_add_u32_e32 v40, s16, v40
	v_lshl_add_u64 v[48:49], v[42:43], 0, v[48:49]
	s_waitcnt vmcnt(1)
	v_lshlrev_b32_e32 v60, 16, v34
	v_and_b32_e32 v61, 0xffff0000, v34
	v_lshlrev_b32_e32 v62, 16, v32
	v_and_b32_e32 v63, 0xffff0000, v32
	v_lshlrev_b32_e32 v56, 16, v35
	v_and_b32_e32 v57, 0xffff0000, v35
	v_lshlrev_b32_e32 v34, 16, v33
	v_and_b32_e32 v35, 0xffff0000, v33
	v_mov_b32_e32 v32, v60
	v_mov_b32_e32 v33, v62
	v_mov_b32_e32 v66, v61
	v_mov_b32_e32 v67, v63
	v_pk_add_f32 v[32:33], v[32:33], v[66:67]
	v_mov_b32_e32 v66, v56
	v_mov_b32_e32 v67, v34
	s_waitcnt vmcnt(0)
	v_lshlrev_b32_e32 v51, 16, v36
	v_lshlrev_b32_e32 v50, 16, v38
	v_and_b32_e32 v53, 0xffff0000, v36
	v_and_b32_e32 v52, 0xffff0000, v38
	v_pk_add_f32 v[32:33], v[32:33], v[66:67]
	v_mov_b32_e32 v66, v57
	v_mov_b32_e32 v67, v35
	v_lshlrev_b32_e32 v55, 16, v37
	v_lshlrev_b32_e32 v54, 16, v39
	v_and_b32_e32 v36, 0xffff0000, v39
	v_pk_add_f32 v[38:39], v[50:51], v[52:53]
	v_pk_add_f32 v[32:33], v[32:33], v[66:67]
	v_and_b32_e32 v37, 0xffff0000, v37
	v_pk_add_f32 v[38:39], v[38:39], v[54:55]
	v_add_f32_e32 v33, 0, v33
	v_pk_add_f32 v[38:39], v[38:39], v[36:37]
	v_add_f32_e32 v32, v32, v33
	v_add_f32_e32 v32, v39, v32
	v_add_f32_e32 v32, v38, v32
	v_mov_b32_e32 v74, v50
	v_mov_b32_e32 v75, v52
	v_mov_b32_e32 v52, v51
	s_waitcnt lgkmcnt(0)
	s_nop 1
	v_add_f32_dpp v32, v32, v32 quad_perm:[1,0,3,2] row_mask:0xf bank_mask:0xf
	s_nop 1
	v_add_f32_dpp v32, v32, v32 quad_perm:[2,3,0,1] row_mask:0xf bank_mask:0xf
	s_nop 1
	v_add_f32_dpp v32, v32, v32 row_half_mirror row_mask:0xf bank_mask:0xf
	s_nop 1
	v_add_f32_dpp v32, v32, v32 row_mirror row_mask:0xf bank_mask:0xf
	s_nop 1
	v_add_f32_dpp v32, v32, v32 row_bcast:15 row_mask:0xa bank_mask:0xf
	s_nop 1
	v_add_f32_dpp v32, v32, v32 row_bcast:31 row_mask:0xc bank_mask:0xf
	s_nop 1
	v_readlane_b32 s98, v32, 63
	s_nop 1
	v_mov_b32_e32 v32, s98
	v_mul_f32_e32 v32, 0x3a800000, v32
	v_pk_add_f32 v[38:39], v[62:63], v[32:33] op_sel_hi:[1,0] neg_lo:[0,1] neg_hi:[0,1]
	v_pk_add_f32 v[60:61], v[60:61], v[32:33] op_sel_hi:[1,0] neg_lo:[0,1] neg_hi:[0,1]
	v_mov_b32_e32 v66, v39
	v_mov_b32_e32 v67, v61
	v_pk_add_f32 v[34:35], v[34:35], v[32:33] op_sel_hi:[1,0] neg_lo:[0,1] neg_hi:[0,1]
	v_pk_add_f32 v[56:57], v[56:57], v[32:33] op_sel_hi:[1,0] neg_lo:[0,1] neg_hi:[0,1]
	v_mov_b32_e32 v62, v38
	v_mov_b32_e32 v63, v60
	v_pk_mul_f32 v[66:67], v[66:67], v[66:67]
	v_pk_add_f32 v[74:75], v[74:75], v[32:33] op_sel_hi:[1,0] neg_lo:[0,1] neg_hi:[0,1]
	v_pk_fma_f32 v[62:63], v[62:63], v[62:63], v[66:67]
	v_mov_b32_e32 v66, v34
	v_mov_b32_e32 v67, v56
	v_pk_fma_f32 v[62:63], v[66:67], v[66:67], v[62:63]
	v_mov_b32_e32 v66, v35
	v_mov_b32_e32 v67, v57
	v_pk_add_f32 v[50:51], v[52:53], v[32:33] op_sel_hi:[1,0] neg_lo:[0,1] neg_hi:[0,1]
	v_pk_fma_f32 v[62:63], v[66:67], v[66:67], v[62:63]
	v_mov_b32_e32 v66, v54
	v_mov_b32_e32 v67, v36
	v_mov_b32_e32 v36, v55
	v_mov_b32_e32 v76, v75
	v_mov_b32_e32 v77, v51
	v_pk_add_f32 v[66:67], v[66:67], v[32:33] op_sel_hi:[1,0] neg_lo:[0,1] neg_hi:[0,1]
	v_pk_add_f32 v[54:55], v[36:37], v[32:33] op_sel_hi:[1,0] neg_lo:[0,1] neg_hi:[0,1]
	v_mov_b32_e32 v52, v74
	v_mov_b32_e32 v53, v50
	v_pk_mul_f32 v[76:77], v[76:77], v[76:77]
	v_mov_b32_e32 v32, v66
	v_mov_b32_e32 v33, v54
	v_pk_fma_f32 v[52:53], v[52:53], v[52:53], v[76:77]
	v_mov_b32_e32 v36, v67
	v_mov_b32_e32 v37, v55
	v_pk_fma_f32 v[32:33], v[32:33], v[32:33], v[52:53]
	s_nop 0
	v_pk_fma_f32 v[32:33], v[36:37], v[36:37], v[32:33]
	v_add_f32_e32 v36, v62, v63
	v_add_f32_e32 v33, v33, v36
	v_add_f32_e32 v32, v32, v33
	s_waitcnt lgkmcnt(0)
	s_nop 1
	v_add_f32_dpp v32, v32, v32 quad_perm:[1,0,3,2] row_mask:0xf bank_mask:0xf
	s_nop 1
	v_add_f32_dpp v32, v32, v32 quad_perm:[2,3,0,1] row_mask:0xf bank_mask:0xf
	s_nop 1
	v_add_f32_dpp v32, v32, v32 row_half_mirror row_mask:0xf bank_mask:0xf
	s_nop 1
	v_add_f32_dpp v32, v32, v32 row_mirror row_mask:0xf bank_mask:0xf
	s_nop 1
	v_add_f32_dpp v32, v32, v32 row_bcast:15 row_mask:0xa bank_mask:0xf
	s_nop 1
	v_add_f32_dpp v32, v32, v32 row_bcast:31 row_mask:0xc bank_mask:0xf
	s_nop 1
	v_readlane_b32 s98, v32, 63
	s_nop 1
	v_mov_b32_e32 v32, s98
	v_fmamk_f32 v32, v32, 0x3a800000, v206
	v_cmp_gt_f32_e32 vcc, s24, v32
	v_mul_f32_e32 v33, 0x4b800000, v32
	s_nop 0
	v_cndmask_b32_e32 v32, v32, v33, vcc
	v_rsq_f32_e32 v32, v32
	s_nop 0
	v_mul_f32_e32 v33, 0x45800000, v32
	v_cndmask_b32_e32 v58, v32, v33, vcc
	v_pk_mul_f32 v[32:33], v[38:39], v[58:59] op_sel_hi:[1,0]
	v_pk_mul_f32 v[34:35], v[34:35], v[58:59] op_sel_hi:[1,0]
	v_pk_mul_f32 v[36:37], v[60:61], v[58:59] op_sel_hi:[1,0]
	v_pk_mul_f32 v[38:39], v[56:57], v[58:59] op_sel_hi:[1,0]
	v_pk_fma_f32 v[32:33], v[4:5], v[32:33], v[12:13]
	v_pk_fma_f32 v[34:35], v[6:7], v[34:35], v[14:15]
	v_pk_fma_f32 v[36:37], v[0:1], v[36:37], v[8:9]
	v_pk_fma_f32 v[38:39], v[2:3], v[38:39], v[10:11]
	v_pk_mul_f32 v[50:51], v[50:51], v[58:59] op_sel_hi:[1,0]
	v_pk_mul_f32 v[52:53], v[54:55], v[58:59] op_sel_hi:[1,0]
	v_pk_mul_f32 v[54:55], v[74:75], v[58:59] op_sel_hi:[1,0]
	v_pk_mul_f32 v[56:57], v[66:67], v[58:59] op_sel_hi:[1,0]
	v_pk_fma_f32 v[50:51], v[20:21], v[50:51], v[28:29]
; DI unsigned pack2(float lo, float hi) { f2v_ f = {lo, hi}; b2v_ b = __builtin_convertvector(f, b2v_); return __builtin_bit_cast(unsigned, b); }
; __device__ __forceinline__ void rowpass(const Params& p, int mode, const float* __restrict__ lg, const float* __restrict__ lb,
;                         const float* __restrict__ modl, int shoff, int scoff) {
;     ...
; #pragma unroll
;       for (int k = 0; k < 4; ++k) {
;         const int c = CK(k);
;         const float4 g = *(const float4*)(lg + c), be = *(const float4*)(lb + c);
;         v[k].x = v[k].x * rstd * g.x + be.x; v[k].y = v[k].y * rstd * g.y + be.y;
;         v[k].z = v[k].z * rstd * g.z + be.z; v[k].w = v[k].w * rstd * g.w + be.w;
;         if ((mode & 2) && n >= CTXL) *(float4*)(p.out + ((size_t)b * SEQ + (n - CTXL)) * D + c) = v[k];
;       }
;       if (!(mode & 16)) {
; #pragma unroll
;         for (int i = 0; i < 2; ++i) {
;           u32x4 w;
;           w.x = pack2(v[2 * i].x, v[2 * i].y); w.y = pack2(v[2 * i].z, v[2 * i].w);
;           w.z = pack2(v[2 * i + 1].x, v[2 * i + 1].y); w.w = pack2(v[2 * i + 1].z, v[2 * i + 1].w);
;           *(u32x4*)(xr + i * 512 + lane * 8) = w;
;         }
;       }
;     }
;     if (mode & 4) {
;       float s = 0.f;
; #pragma unroll
;       for (int i = 0; i < 4; ++i) s += v[i].x + v[i].y + v[i].z + v[i].w;
;       const float mu = wave_sum(s) * (1.f / D);
	v_pk_fma_f32 v[52:53], v[22:23], v[52:53], v[30:31]
	v_pk_fma_f32 v[54:55], v[54:55], v[16:17], v[24:25]
	v_pk_fma_f32 v[56:57], v[56:57], v[18:19], v[26:27]
	v_cvt_pk_bf16_f32 v60, v32, v33
	v_cvt_pk_bf16_f32 v61, v34, v35
	v_cvt_pk_bf16_f32 v62, v36, v37
	v_cvt_pk_bf16_f32 v63, v38, v39
	global_store_dwordx4 v[64:65], v[60:63], off
	s_nop 1
	v_cvt_pk_bf16_f32 v60, v50, v51
	v_cvt_pk_bf16_f32 v61, v52, v53
	v_cvt_pk_bf16_f32 v62, v54, v55
	v_cvt_pk_bf16_f32 v63, v56, v57
	global_store_dwordx4 v[64:65], v[60:63], off offset:1024
	s_nop 1
	v_mov_b32_e32 v60, v36
	v_mov_b32_e32 v61, v32
	v_mov_b32_e32 v62, v37
	v_mov_b32_e32 v63, v33
	v_pk_add_f32 v[60:61], v[60:61], v[62:63]
	v_mov_b32_e32 v62, v38
	v_mov_b32_e32 v63, v34
	v_pk_add_f32 v[60:61], v[62:63], v[60:61]
	v_mov_b32_e32 v62, v39
	v_mov_b32_e32 v63, v35
	v_pk_add_f32 v[60:61], v[62:63], v[60:61]
	v_mov_b32_e32 v62, v51
	v_add_f32_e32 v41, 0, v61
	v_add_f32_e32 v41, v60, v41
	v_mov_b32_e32 v60, v50
	v_mov_b32_e32 v61, v54
	v_mov_b32_e32 v63, v55
	v_pk_add_f32 v[60:61], v[60:61], v[62:63]
	v_mov_b32_e32 v62, v52
	v_mov_b32_e32 v63, v56
	v_pk_add_f32 v[60:61], v[62:63], v[60:61]
	v_mov_b32_e32 v62, v53
	v_mov_b32_e32 v63, v57
	v_pk_add_f32 v[60:61], v[62:63], v[60:61]
	s_nop 0
	v_add_f32_e32 v41, v60, v41
	v_add_f32_e32 v41, v41, v61
	v_mul_hi_i32_i24_e32 v61, 0x6000, v47
	v_mul_i32_i24_e32 v60, 0x6000, v47
	v_lshl_add_u64 v[62:63], s[8:9], 0, v[60:61]
	v_lshl_add_u64 v[60:61], v[62:63], 0, s[38:39]
	v_lshl_add_u64 v[66:67], v[62:63], 0, s[14:15]
	v_mov_b32_e32 v47, v161
	v_lshl_add_u64 v[64:65], v[60:61], 0, v[160:161]
	v_lshl_add_u64 v[62:63], v[66:67], 0, v[160:161]
	v_lshl_add_u64 v[60:61], v[60:61], 0, v[46:47]
	v_lshl_add_u64 v[66:67], v[66:67], 0, v[46:47]
	global_load_dwordx4 v[74:77], v[60:61], off offset:16
	global_load_dwordx4 v[78:81], v[60:61], off
	global_load_dwordx4 v[82:85], v[66:67], off offset:16
	global_load_dwordx4 v[86:89], v[66:67], off
	s_waitcnt lgkmcnt(0)
	s_nop 1
	v_add_f32_dpp v41, v41, v41 quad_perm:[1,0,3,2] row_mask:0xf bank_mask:0xf
	s_nop 1
	v_add_f32_dpp v41, v41, v41 quad_perm:[2,3,0,1] row_mask:0xf bank_mask:0xf
	s_nop 1
	v_add_f32_dpp v41, v41, v41 row_half_mirror row_mask:0xf bank_mask:0xf
	s_nop 1
	v_add_f32_dpp v41, v41, v41 row_mirror row_mask:0xf bank_mask:0xf
	s_nop 1
	v_add_f32_dpp v41, v41, v41 row_bcast:15 row_mask:0xa bank_mask:0xf
	s_nop 1
	v_add_f32_dpp v41, v41, v41 row_bcast:31 row_mask:0xc bank_mask:0xf
	s_nop 1
	v_readlane_b32 s98, v41, 63
	s_nop 1
	v_mov_b32_e32 v41, s98
	v_mul_f32_e32 v58, 0x3a800000, v41
	v_pk_add_f32 v[92:93], v[54:55], v[58:59] op_sel_hi:[1,0] neg_lo:[0,1] neg_hi:[0,1]
	v_pk_add_f32 v[96:97], v[50:51], v[58:59] op_sel_hi:[1,0] neg_lo:[0,1] neg_hi:[0,1]
	v_pk_add_f32 v[90:91], v[56:57], v[58:59] op_sel_hi:[1,0] neg_lo:[0,1] neg_hi:[0,1]
	v_mov_b32_e32 v56, v93
	v_mov_b32_e32 v57, v97
	v_pk_add_f32 v[94:95], v[52:53], v[58:59] op_sel_hi:[1,0] neg_lo:[0,1] neg_hi:[0,1]
	v_mov_b32_e32 v54, v92
	v_mov_b32_e32 v55, v96
	v_pk_mul_f32 v[56:57], v[56:57], v[56:57]
	v_mov_b32_e32 v50, v90
	v_mov_b32_e32 v51, v94
	v_pk_fma_f32 v[54:55], v[54:55], v[54:55], v[56:57]
	v_mov_b32_e32 v52, v91
	v_mov_b32_e32 v53, v95
	v_pk_fma_f32 v[50:51], v[50:51], v[50:51], v[54:55]
	v_pk_add_f32 v[36:37], v[36:37], v[58:59] op_sel_hi:[1,0] neg_lo:[0,1] neg_hi:[0,1]
	v_pk_fma_f32 v[98:99], v[52:53], v[52:53], v[50:51]
	global_load_dwordx4 v[50:53], v[64:65], off offset:16
	global_load_dwordx4 v[54:57], v[64:65], off
	s_nop 0
	global_load_dwordx4 v[64:67], v[62:63], off offset:16
	s_nop 0
	global_load_dwordx4 v[60:63], v[62:63], off
	v_pk_add_f32 v[32:33], v[32:33], v[58:59] op_sel_hi:[1,0] neg_lo:[0,1] neg_hi:[0,1]
	v_mov_b32_e32 v107, v37
	v_mov_b32_e32 v106, v33
	v_pk_add_f32 v[38:39], v[38:39], v[58:59] op_sel_hi:[1,0] neg_lo:[0,1] neg_hi:[0,1]
	v_pk_add_f32 v[34:35], v[34:35], v[58:59] op_sel_hi:[1,0] neg_lo:[0,1] neg_hi:[0,1]
	v_mov_b32_e32 v104, v32
	v_mov_b32_e32 v105, v36
	v_pk_mul_f32 v[106:107], v[106:107], v[106:107]
	v_mov_b32_e32 v100, v34
	v_mov_b32_e32 v101, v38
	v_pk_fma_f32 v[104:105], v[104:105], v[104:105], v[106:107]
	v_mov_b32_e32 v102, v35
	v_mov_b32_e32 v103, v39
	v_pk_fma_f32 v[100:101], v[100:101], v[100:101], v[104:105]
	s_waitcnt vmcnt(5)
; DI unsigned pack2(float lo, float hi) { f2v_ f = {lo, hi}; b2v_ b = __builtin_convertvector(f, b2v_); return __builtin_bit_cast(unsigned, b); }
; __device__ __forceinline__ void rowpass(const Params& p, int mode, const float* __restrict__ lg, const float* __restrict__ lb,
;                         const float* __restrict__ modl, int shoff, int scoff) {
;     ...
;       const float mu = wave_sum(s) * (1.f / D);
;       float q = 0.f;
; #pragma unroll
;       for (int i = 0; i < 4; ++i) {
;         v[i].x -= mu; v[i].y -= mu; v[i].z -= mu; v[i].w -= mu;
;         q += v[i].x * v[i].x + v[i].y * v[i].y + v[i].z * v[i].z + v[i].w * v[i].w;
;       }
;       const float rstd = rsqrtf(wave_sum(q) * (1.f / D) + LN_EPS);
;       const float* mr = modl + (size_t)mi * 6144;
;       unsigned ow[8];
; #pragma unroll
;       for (int k = 0; k < 4; ++k) {
;         const int c = CK(k);
;         const float4 sh = *(const float4*)(mr + shoff + c), sc = *(const float4*)(mr + scoff + c);
;         ow[2 * k] = pack2(v[k].x * rstd * (1.f + sc.x) + sh.x, v[k].y * rstd * (1.f + sc.y) + sh.y);
;         ow[2 * k + 1] = pack2(v[k].z * rstd * (1.f + sc.z) + sh.z, v[k].w * rstd * (1.f + sc.w) + sh.w);
;       }
; #pragma unroll
;       for (int i = 0; i < 2; ++i) {
;         const u32x4 w = {ow[4 * i], ow[4 * i + 1], ow[4 * i + 2], ow[4 * i + 3]};
;         *(u32x4*)(XN + (size_t)row * D + i * 512 + lane * 8) = w;
;       }
	v_pk_add_f32 v[82:83], v[82:83], 1.0 op_sel_hi:[1,0]
	v_pk_fma_f32 v[100:101], v[102:103], v[102:103], v[100:101]
	s_waitcnt vmcnt(4)
	v_pk_add_f32 v[88:89], v[88:89], 1.0 op_sel_hi:[1,0]
	v_add_f32_e32 v41, v100, v101
	v_add_f32_e32 v41, v99, v41
	v_add_f32_e32 v41, v98, v41
	v_pk_add_f32 v[86:87], v[86:87], 1.0 op_sel_hi:[1,0]
	s_waitcnt vmcnt(1)
	v_pk_add_f32 v[66:67], v[66:67], 1.0 op_sel_hi:[1,0]
	s_waitcnt vmcnt(0)
	v_pk_add_f32 v[62:63], v[62:63], 1.0 op_sel_hi:[1,0]
	s_waitcnt lgkmcnt(0)
	s_nop 1
	v_add_f32_dpp v41, v41, v41 quad_perm:[1,0,3,2] row_mask:0xf bank_mask:0xf
	s_nop 1
	v_add_f32_dpp v41, v41, v41 quad_perm:[2,3,0,1] row_mask:0xf bank_mask:0xf
	s_nop 1
	v_add_f32_dpp v41, v41, v41 row_half_mirror row_mask:0xf bank_mask:0xf
	s_nop 1
	v_add_f32_dpp v41, v41, v41 row_mirror row_mask:0xf bank_mask:0xf
	s_nop 1
	v_add_f32_dpp v41, v41, v41 row_bcast:15 row_mask:0xa bank_mask:0xf
	s_nop 1
	v_add_f32_dpp v41, v41, v41 row_bcast:31 row_mask:0xc bank_mask:0xf
	s_nop 1
	v_readlane_b32 s98, v41, 63
	s_nop 1
	v_mov_b32_e32 v41, s98
	v_fmamk_f32 v41, v41, 0x3a800000, v206
	v_cmp_gt_f32_e32 vcc, s24, v41
	v_mul_f32_e32 v47, 0x4b800000, v41
	v_pk_add_f32 v[60:61], v[60:61], 1.0 op_sel_hi:[1,0]
	v_cndmask_b32_e32 v41, v41, v47, vcc
	v_rsq_f32_e32 v41, v41
	v_pk_add_f32 v[64:65], v[64:65], 1.0 op_sel_hi:[1,0]
	v_mul_f32_e32 v47, 0x45800000, v41
	v_cndmask_b32_e32 v58, v41, v47, vcc
	v_pk_mul_f32 v[32:33], v[32:33], v[58:59] op_sel_hi:[1,0]
	v_pk_mul_f32 v[34:35], v[34:35], v[58:59] op_sel_hi:[1,0]
	v_pk_fma_f32 v[32:33], v[60:61], v[32:33], v[54:55]
	v_pk_fma_f32 v[34:35], v[62:63], v[34:35], v[56:57]
	v_cvt_pk_bf16_f32 v32, v32, v33
	v_cvt_pk_bf16_f32 v33, v34, v35
	v_pk_mul_f32 v[34:35], v[36:37], v[58:59] op_sel_hi:[1,0]
	v_pk_mul_f32 v[36:37], v[38:39], v[58:59] op_sel_hi:[1,0]
	v_pk_fma_f32 v[34:35], v[64:65], v[34:35], v[50:51]
	v_pk_fma_f32 v[36:37], v[66:67], v[36:37], v[52:53]
	v_cvt_pk_bf16_f32 v34, v34, v35
	v_cvt_pk_bf16_f32 v35, v36, v37
	v_pk_mul_f32 v[36:37], v[96:97], v[58:59] op_sel_hi:[1,0]
	v_pk_mul_f32 v[38:39], v[94:95], v[58:59] op_sel_hi:[1,0]
	v_pk_fma_f32 v[36:37], v[36:37], v[86:87], v[78:79]
	v_pk_fma_f32 v[38:39], v[38:39], v[88:89], v[80:81]
	v_cvt_pk_bf16_f32 v36, v36, v37
	v_cvt_pk_bf16_f32 v37, v38, v39
	v_pk_mul_f32 v[38:39], v[92:93], v[58:59] op_sel_hi:[1,0]
	v_pk_mul_f32 v[50:51], v[90:91], v[58:59] op_sel_hi:[1,0]
	v_pk_add_f32 v[52:53], v[84:85], 1.0 op_sel_hi:[1,0]
	v_cmp_lt_i32_e32 vcc, s43, v40
	v_pk_fma_f32 v[38:39], v[38:39], v[82:83], v[74:75]
	v_pk_fma_f32 v[50:51], v[50:51], v[52:53], v[76:77]
	s_or_b64 s[12:13], vcc, s[12:13]
	v_cvt_pk_bf16_f32 v38, v38, v39
	v_cvt_pk_bf16_f32 v39, v50, v51
	global_store_dwordx4 v[48:49], v[32:35], off
	global_store_dwordx4 v[48:49], v[36:39], off offset:1024
	s_andn2_b64 exec, exec, s[12:13]
	s_cbranch_execnz .LBB0_1302

; __device__ __forceinline__ void rowpass(const Params& p, int mode, const float* __restrict__ lg, const float* __restrict__ lb,
;                         const float* __restrict__ modl, int shoff, int scoff) {
;     ...
; #pragma unroll
;       for (int i = 0; i < 2; ++i) {
;         const u32x4 w = *(const u32x4*)(xr + i * 512 + lane * 8);
;         v[2 * i].x = __uint_as_float(w.x << 16); v[2 * i].y = __uint_as_float(w.x & 0xffff0000u);
;         v[2 * i].z = __uint_as_float(w.y << 16); v[2 * i].w = __uint_as_float(w.y & 0xffff0000u);
;         v[2 * i + 1].x = __uint_as_float(w.z << 16); v[2 * i + 1].y = __uint_as_float(w.z & 0xffff0000u);
;         v[2 * i + 1].z = __uint_as_float(w.w << 16); v[2 * i + 1].w = __uint_as_float(w.w & 0xffff0000u);
;       }
;     }
;     if (mode & 1) {
;       float s = 0.f;
; #pragma unroll
;       for (int i = 0; i < 4; ++i) s += v[i].x + v[i].y + v[i].z + v[i].w;
;       const float mu = wave_sum(s) * (1.f / D);
;       float q = 0.f;
; #pragma unroll
;       for (int i = 0; i < 4; ++i) {
;         v[i].x -= mu; v[i].y -= mu; v[i].z -= mu; v[i].w -= mu;
;         q += v[i].x * v[i].x + v[i].y * v[i].y + v[i].z * v[i].z + v[i].w * v[i].w;
;       }
;       const float rstd = rsqrtf(wave_sum(q) * (1.f / D) + LN_EPS);
.LBB0_1410:
	v_mul_hi_i32 v32, v40, s15
	v_lshrrev_b32_e32 v33, 31, v32
	v_ashrrev_i32_e32 v32, 11, v32
	v_add_u32_e32 v32, v32, v33
	v_mul_i32_i24_e32 v33, 0x1100, v32
	v_ashrrev_i32_e32 v41, 31, v40
	v_sub_u32_e32 v33, v40, v33
	v_lshlrev_b64 v[48:49], 11, v[40:41]
	v_cmp_lt_i32_e32 vcc, s2, v33
	v_lshl_add_u64 v[64:65], v[44:45], 0, v[48:49]
	s_mov_b64 s[12:13], 0x1000
	v_cndmask_b32_e32 v47, 16, v32, vcc
	global_load_dwordx4 v[32:35], v[64:65], off
	global_load_dwordx4 v[36:39], v[64:65], off offset:1024
	v_add_u32_e32 v40, s14, v40
	v_lshl_add_u64 v[48:49], v[42:43], 0, v[48:49]
	s_waitcnt vmcnt(1)
	v_lshlrev_b32_e32 v60, 16, v34
	v_and_b32_e32 v61, 0xffff0000, v34
	v_lshlrev_b32_e32 v62, 16, v32
	v_and_b32_e32 v63, 0xffff0000, v32
	v_lshlrev_b32_e32 v56, 16, v35
	v_and_b32_e32 v57, 0xffff0000, v35
	v_lshlrev_b32_e32 v34, 16, v33
	v_and_b32_e32 v35, 0xffff0000, v33
	v_mov_b32_e32 v32, v60
	v_mov_b32_e32 v33, v62
	v_mov_b32_e32 v72, v61
	v_mov_b32_e32 v73, v63
	v_pk_add_f32 v[32:33], v[32:33], v[72:73]
	v_mov_b32_e32 v72, v56
	v_mov_b32_e32 v73, v34
	s_waitcnt vmcnt(0)
	v_lshlrev_b32_e32 v51, 16, v36
	v_lshlrev_b32_e32 v50, 16, v38
	v_and_b32_e32 v53, 0xffff0000, v36
	v_and_b32_e32 v52, 0xffff0000, v38
	v_pk_add_f32 v[32:33], v[32:33], v[72:73]
	v_mov_b32_e32 v72, v57
	v_mov_b32_e32 v73, v35
	v_lshlrev_b32_e32 v55, 16, v37
	v_lshlrev_b32_e32 v54, 16, v39
	v_and_b32_e32 v36, 0xffff0000, v39
	v_pk_add_f32 v[38:39], v[50:51], v[52:53]
	v_pk_add_f32 v[32:33], v[32:33], v[72:73]
	v_and_b32_e32 v37, 0xffff0000, v37
	v_pk_add_f32 v[38:39], v[38:39], v[54:55]
	v_add_f32_e32 v33, 0, v33
	v_pk_add_f32 v[38:39], v[38:39], v[36:37]
	v_add_f32_e32 v32, v32, v33
	v_add_f32_e32 v32, v39, v32
	v_add_f32_e32 v32, v38, v32
	v_mov_b32_e32 v74, v50
	v_mov_b32_e32 v75, v52
	v_mov_b32_e32 v52, v51
	s_waitcnt lgkmcnt(0)
	s_nop 1
	v_add_f32_dpp v32, v32, v32 quad_perm:[1,0,3,2] row_mask:0xf bank_mask:0xf
	s_nop 1
	v_add_f32_dpp v32, v32, v32 quad_perm:[2,3,0,1] row_mask:0xf bank_mask:0xf
	s_nop 1
	v_add_f32_dpp v32, v32, v32 row_half_mirror row_mask:0xf bank_mask:0xf
	s_nop 1
	v_add_f32_dpp v32, v32, v32 row_mirror row_mask:0xf bank_mask:0xf
	s_nop 1
	v_add_f32_dpp v32, v32, v32 row_bcast:15 row_mask:0xa bank_mask:0xf
	s_nop 1
	v_add_f32_dpp v32, v32, v32 row_bcast:31 row_mask:0xc bank_mask:0xf
	s_nop 1
	v_readlane_b32 s98, v32, 63
	s_nop 1
	v_mov_b32_e32 v32, s98
	v_mul_f32_e32 v32, 0x3a800000, v32
	v_pk_add_f32 v[38:39], v[62:63], v[32:33] op_sel_hi:[1,0] neg_lo:[0,1] neg_hi:[0,1]
	v_pk_add_f32 v[60:61], v[60:61], v[32:33] op_sel_hi:[1,0] neg_lo:[0,1] neg_hi:[0,1]
	v_mov_b32_e32 v72, v39
	v_mov_b32_e32 v73, v61
	v_pk_add_f32 v[34:35], v[34:35], v[32:33] op_sel_hi:[1,0] neg_lo:[0,1] neg_hi:[0,1]
	v_pk_add_f32 v[56:57], v[56:57], v[32:33] op_sel_hi:[1,0] neg_lo:[0,1] neg_hi:[0,1]
	v_mov_b32_e32 v62, v38
	v_mov_b32_e32 v63, v60
	v_pk_mul_f32 v[72:73], v[72:73], v[72:73]
	v_pk_add_f32 v[74:75], v[74:75], v[32:33] op_sel_hi:[1,0] neg_lo:[0,1] neg_hi:[0,1]
	v_pk_fma_f32 v[62:63], v[62:63], v[62:63], v[72:73]
	v_mov_b32_e32 v72, v34
	v_mov_b32_e32 v73, v56
	v_pk_fma_f32 v[62:63], v[72:73], v[72:73], v[62:63]
	v_mov_b32_e32 v72, v35
	v_mov_b32_e32 v73, v57
	v_pk_add_f32 v[50:51], v[52:53], v[32:33] op_sel_hi:[1,0] neg_lo:[0,1] neg_hi:[0,1]
	v_pk_fma_f32 v[62:63], v[72:73], v[72:73], v[62:63]
	v_mov_b32_e32 v72, v54
	v_mov_b32_e32 v73, v36
	v_mov_b32_e32 v36, v55
	v_mov_b32_e32 v76, v75
	v_mov_b32_e32 v77, v51
	v_pk_add_f32 v[72:73], v[72:73], v[32:33] op_sel_hi:[1,0] neg_lo:[0,1] neg_hi:[0,1]
	v_pk_add_f32 v[54:55], v[36:37], v[32:33] op_sel_hi:[1,0] neg_lo:[0,1] neg_hi:[0,1]
	v_mov_b32_e32 v52, v74
	v_mov_b32_e32 v53, v50
	v_pk_mul_f32 v[76:77], v[76:77], v[76:77]
	v_mov_b32_e32 v32, v72
	v_mov_b32_e32 v33, v54
	v_pk_fma_f32 v[52:53], v[52:53], v[52:53], v[76:77]
	v_mov_b32_e32 v36, v73
	v_mov_b32_e32 v37, v55
	v_pk_fma_f32 v[32:33], v[32:33], v[32:33], v[52:53]
	s_nop 0
	v_pk_fma_f32 v[32:33], v[36:37], v[36:37], v[32:33]
	v_add_f32_e32 v36, v62, v63
	v_add_f32_e32 v33, v33, v36
	v_add_f32_e32 v32, v32, v33
	s_waitcnt lgkmcnt(0)
	s_nop 1
	v_add_f32_dpp v32, v32, v32 quad_perm:[1,0,3,2] row_mask:0xf bank_mask:0xf
	s_nop 1
	v_add_f32_dpp v32, v32, v32 quad_perm:[2,3,0,1] row_mask:0xf bank_mask:0xf
	s_nop 1
	v_add_f32_dpp v32, v32, v32 row_half_mirror row_mask:0xf bank_mask:0xf
	s_nop 1
	v_add_f32_dpp v32, v32, v32 row_mirror row_mask:0xf bank_mask:0xf
	s_nop 1
	v_add_f32_dpp v32, v32, v32 row_bcast:15 row_mask:0xa bank_mask:0xf
	s_nop 1
	v_add_f32_dpp v32, v32, v32 row_bcast:31 row_mask:0xc bank_mask:0xf
	s_nop 1
	v_readlane_b32 s98, v32, 63
	s_nop 1
	v_mov_b32_e32 v32, s98
	v_fmamk_f32 v32, v32, 0x3a800000, v206
	v_cmp_gt_f32_e32 vcc, s16, v32
	v_mul_f32_e32 v33, 0x4b800000, v32
	s_nop 0
	v_cndmask_b32_e32 v32, v32, v33, vcc
	v_rsq_f32_e32 v32, v32
	s_nop 0
	v_mul_f32_e32 v33, 0x45800000, v32
	v_cndmask_b32_e32 v58, v32, v33, vcc
	v_pk_mul_f32 v[32:33], v[38:39], v[58:59] op_sel_hi:[1,0]
	v_pk_mul_f32 v[34:35], v[34:35], v[58:59] op_sel_hi:[1,0]
	v_pk_mul_f32 v[36:37], v[60:61], v[58:59] op_sel_hi:[1,0]
	v_pk_mul_f32 v[38:39], v[56:57], v[58:59] op_sel_hi:[1,0]
	v_pk_fma_f32 v[32:33], v[4:5], v[32:33], v[12:13]
	v_pk_fma_f32 v[34:35], v[6:7], v[34:35], v[14:15]
	v_pk_fma_f32 v[36:37], v[0:1], v[36:37], v[8:9]
	v_pk_fma_f32 v[38:39], v[2:3], v[38:39], v[10:11]
	v_pk_mul_f32 v[50:51], v[50:51], v[58:59] op_sel_hi:[1,0]
	v_pk_mul_f32 v[52:53], v[54:55], v[58:59] op_sel_hi:[1,0]
	v_pk_mul_f32 v[54:55], v[74:75], v[58:59] op_sel_hi:[1,0]
	v_pk_mul_f32 v[56:57], v[72:73], v[58:59] op_sel_hi:[1,0]
	v_pk_fma_f32 v[50:51], v[20:21], v[50:51], v[28:29]
; DI unsigned pack2(float lo, float hi) { f2v_ f = {lo, hi}; b2v_ b = __builtin_convertvector(f, b2v_); return __builtin_bit_cast(unsigned, b); }
; __device__ __forceinline__ void rowpass(const Params& p, int mode, const float* __restrict__ lg, const float* __restrict__ lb,
;                         const float* __restrict__ modl, int shoff, int scoff) {
;     ...
; #pragma unroll
;       for (int k = 0; k < 4; ++k) {
;         const int c = CK(k);
;         const float4 g = *(const float4*)(lg + c), be = *(const float4*)(lb + c);
;         v[k].x = v[k].x * rstd * g.x + be.x; v[k].y = v[k].y * rstd * g.y + be.y;
;         v[k].z = v[k].z * rstd * g.z + be.z; v[k].w = v[k].w * rstd * g.w + be.w;
;         if ((mode & 2) && n >= CTXL) *(float4*)(p.out + ((size_t)b * SEQ + (n - CTXL)) * D + c) = v[k];
;       }
;       if (!(mode & 16)) {
; #pragma unroll
;         for (int i = 0; i < 2; ++i) {
;           u32x4 w;
;           w.x = pack2(v[2 * i].x, v[2 * i].y); w.y = pack2(v[2 * i].z, v[2 * i].w);
;           w.z = pack2(v[2 * i + 1].x, v[2 * i + 1].y); w.w = pack2(v[2 * i + 1].z, v[2 * i + 1].w);
;           *(u32x4*)(xr + i * 512 + lane * 8) = w;
;         }
;       }
;     }
;     if (mode & 4) {
;       float s = 0.f;
; #pragma unroll
;       for (int i = 0; i < 4; ++i) s += v[i].x + v[i].y + v[i].z + v[i].w;
;       const float mu = wave_sum(s) * (1.f / D);
;       float q = 0.f;
; #pragma unroll
;       for (int i = 0; i < 4; ++i) {
;         v[i].x -= mu; v[i].y -= mu; v[i].z -= mu; v[i].w -= mu;
;         q += v[i].x * v[i].x + v[i].y * v[i].y + v[i].z * v[i].z + v[i].w * v[i].w;
;       }
;       const float rstd = rsqrtf(wave_sum(q) * (1.f / D) + LN_EPS);
;       const float* mr = modl + (size_t)mi * 6144;
;       unsigned ow[8];
; #pragma unroll
;       for (int k = 0; k < 4; ++k) {
;         const int c = CK(k);
;         const float4 sh = *(const float4*)(mr + shoff + c), sc = *(const float4*)(mr + scoff + c);
;         ow[2 * k] = pack2(v[k].x * rstd * (1.f + sc.x) + sh.x, v[k].y * rstd * (1.f + sc.y) + sh.y);
;         ow[2 * k + 1] = pack2(v[k].z * rstd * (1.f + sc.z) + sh.z, v[k].w * rstd * (1.f + sc.w) + sh.w);
;       }
; #pragma unroll
;       for (int i = 0; i < 2; ++i) {
;         const u32x4 w = {ow[4 * i], ow[4 * i + 1], ow[4 * i + 2], ow[4 * i + 3]};
;         *(u32x4*)(XN + (size_t)row * D + i * 512 + lane * 8) = w;
;       }
	v_pk_fma_f32 v[52:53], v[22:23], v[52:53], v[30:31]
	v_pk_fma_f32 v[54:55], v[54:55], v[16:17], v[24:25]
	v_pk_fma_f32 v[56:57], v[56:57], v[18:19], v[26:27]
	v_cvt_pk_bf16_f32 v60, v32, v33
	v_cvt_pk_bf16_f32 v61, v34, v35
	v_cvt_pk_bf16_f32 v62, v36, v37
	v_cvt_pk_bf16_f32 v63, v38, v39
	global_store_dwordx4 v[64:65], v[60:63], off
	s_nop 1
	v_cvt_pk_bf16_f32 v60, v50, v51
	v_cvt_pk_bf16_f32 v61, v52, v53
	v_cvt_pk_bf16_f32 v62, v54, v55
	v_cvt_pk_bf16_f32 v63, v56, v57
	global_store_dwordx4 v[64:65], v[60:63], off offset:1024
	s_nop 1
	v_mov_b32_e32 v60, v36
	v_mov_b32_e32 v61, v32
	v_mov_b32_e32 v62, v37
	v_mov_b32_e32 v63, v33
	v_pk_add_f32 v[60:61], v[60:61], v[62:63]
	v_mov_b32_e32 v62, v38
	v_mov_b32_e32 v63, v34
	v_pk_add_f32 v[60:61], v[62:63], v[60:61]
	v_mov_b32_e32 v62, v39
	v_mov_b32_e32 v63, v35
	v_pk_add_f32 v[60:61], v[62:63], v[60:61]
	v_mov_b32_e32 v62, v51
	v_add_f32_e32 v41, 0, v61
	v_add_f32_e32 v41, v60, v41
	v_mov_b32_e32 v60, v50
	v_mov_b32_e32 v61, v54
	v_mov_b32_e32 v63, v55
	v_pk_add_f32 v[60:61], v[60:61], v[62:63]
	v_mov_b32_e32 v62, v52
	v_mov_b32_e32 v63, v56
	v_pk_add_f32 v[60:61], v[62:63], v[60:61]
	v_mov_b32_e32 v62, v53
	v_mov_b32_e32 v63, v57
	v_pk_add_f32 v[60:61], v[62:63], v[60:61]
	s_nop 0
	v_add_f32_e32 v41, v60, v41
	v_add_f32_e32 v41, v41, v61
	v_mul_hi_i32_i24_e32 v61, 0x6000, v47
	v_mul_i32_i24_e32 v60, 0x6000, v47
	v_lshl_add_u64 v[60:61], s[8:9], 0, v[60:61]
	v_lshl_add_u64 v[64:65], v[60:61], 0, s[12:13]
	v_lshl_add_u64 v[62:63], v[60:61], 0, v[160:161]
	v_mov_b32_e32 v47, v161
	v_lshl_add_u64 v[60:61], v[64:65], 0, v[160:161]
	v_lshl_add_u64 v[64:65], v[64:65], 0, v[46:47]
	global_load_dwordx4 v[72:75], v[62:63], off offset:2064
	global_load_dwordx4 v[76:79], v[62:63], off offset:2048
	global_load_dwordx4 v[80:83], v[64:65], off offset:16
	global_load_dwordx4 v[84:87], v[64:65], off
	s_waitcnt lgkmcnt(0)
	s_nop 1
	v_add_f32_dpp v41, v41, v41 quad_perm:[1,0,3,2] row_mask:0xf bank_mask:0xf
	s_nop 1
	v_add_f32_dpp v41, v41, v41 quad_perm:[2,3,0,1] row_mask:0xf bank_mask:0xf
	s_nop 1
	v_add_f32_dpp v41, v41, v41 row_half_mirror row_mask:0xf bank_mask:0xf
	s_nop 1
	v_add_f32_dpp v41, v41, v41 row_mirror row_mask:0xf bank_mask:0xf
	s_nop 1
	v_add_f32_dpp v41, v41, v41 row_bcast:15 row_mask:0xa bank_mask:0xf
	s_nop 1
	v_add_f32_dpp v41, v41, v41 row_bcast:31 row_mask:0xc bank_mask:0xf
	s_nop 1
	v_readlane_b32 s98, v41, 63
	s_nop 1
	v_mov_b32_e32 v41, s98
	v_mul_f32_e32 v58, 0x3a800000, v41
	v_pk_add_f32 v[90:91], v[54:55], v[58:59] op_sel_hi:[1,0] neg_lo:[0,1] neg_hi:[0,1]
	v_pk_add_f32 v[96:97], v[50:51], v[58:59] op_sel_hi:[1,0] neg_lo:[0,1] neg_hi:[0,1]
	v_pk_add_f32 v[88:89], v[56:57], v[58:59] op_sel_hi:[1,0] neg_lo:[0,1] neg_hi:[0,1]
	v_mov_b32_e32 v56, v91
	v_mov_b32_e32 v57, v97
	v_pk_add_f32 v[92:93], v[52:53], v[58:59] op_sel_hi:[1,0] neg_lo:[0,1] neg_hi:[0,1]
	v_mov_b32_e32 v54, v90
	v_mov_b32_e32 v55, v96
	v_pk_mul_f32 v[56:57], v[56:57], v[56:57]
	v_mov_b32_e32 v50, v88
	v_mov_b32_e32 v51, v92
	v_pk_fma_f32 v[54:55], v[54:55], v[54:55], v[56:57]
	v_mov_b32_e32 v52, v89
	v_mov_b32_e32 v53, v93
	v_pk_fma_f32 v[50:51], v[50:51], v[50:51], v[54:55]
	v_pk_add_f32 v[36:37], v[36:37], v[58:59] op_sel_hi:[1,0] neg_lo:[0,1] neg_hi:[0,1]
	v_pk_fma_f32 v[100:101], v[52:53], v[52:53], v[50:51]
	v_pk_add_f32 v[32:33], v[32:33], v[58:59] op_sel_hi:[1,0] neg_lo:[0,1] neg_hi:[0,1]
	v_mov_b32_e32 v107, v37
	v_mov_b32_e32 v106, v33
	v_pk_add_f32 v[38:39], v[38:39], v[58:59] op_sel_hi:[1,0] neg_lo:[0,1] neg_hi:[0,1]
	v_pk_add_f32 v[34:35], v[34:35], v[58:59] op_sel_hi:[1,0] neg_lo:[0,1] neg_hi:[0,1]
	v_mov_b32_e32 v104, v32
	v_mov_b32_e32 v105, v36
	v_pk_mul_f32 v[106:107], v[106:107], v[106:107]
	v_mov_b32_e32 v102, v35
	v_pk_fma_f32 v[104:105], v[104:105], v[104:105], v[106:107]
	v_mov_b32_e32 v103, v39
	s_waitcnt vmcnt(1)
	v_pk_add_f32 v[80:81], v[80:81], 1.0 op_sel_hi:[1,0]
	s_waitcnt vmcnt(0)
	v_pk_add_f32 v[94:95], v[86:87], 1.0 op_sel_hi:[1,0]
	v_pk_add_f32 v[98:99], v[84:85], 1.0 op_sel_hi:[1,0]
	global_load_dwordx4 v[50:53], v[62:63], off offset:16
	global_load_dwordx4 v[54:57], v[62:63], off
	s_nop 0
	global_load_dwordx4 v[62:65], v[60:61], off offset:16
	global_load_dwordx4 v[84:87], v[60:61], off
	s_waitcnt vmcnt(1)
	v_pk_add_f32 v[60:61], v[64:65], 1.0 op_sel_hi:[1,0]
	s_waitcnt vmcnt(0)
	v_pk_add_f32 v[64:65], v[86:87], 1.0 op_sel_hi:[1,0]
	v_mov_b32_e32 v86, v34
	v_mov_b32_e32 v87, v38
	v_pk_fma_f32 v[86:87], v[86:87], v[86:87], v[104:105]
	v_pk_add_f32 v[84:85], v[84:85], 1.0 op_sel_hi:[1,0]
	v_pk_fma_f32 v[86:87], v[102:103], v[102:103], v[86:87]
	v_pk_add_f32 v[62:63], v[62:63], 1.0 op_sel_hi:[1,0]
	v_add_f32_e32 v41, v86, v87
	v_add_f32_e32 v41, v101, v41
	v_add_f32_e32 v41, v100, v41
	s_waitcnt lgkmcnt(0)
	s_nop 1
	v_add_f32_dpp v41, v41, v41 quad_perm:[1,0,3,2] row_mask:0xf bank_mask:0xf
	s_nop 1
	v_add_f32_dpp v41, v41, v41 quad_perm:[2,3,0,1] row_mask:0xf bank_mask:0xf
	s_nop 1
	v_add_f32_dpp v41, v41, v41 row_half_mirror row_mask:0xf bank_mask:0xf
	s_nop 1
	v_add_f32_dpp v41, v41, v41 row_mirror row_mask:0xf bank_mask:0xf
	s_nop 1
	v_add_f32_dpp v41, v41, v41 row_bcast:15 row_mask:0xa bank_mask:0xf
	s_nop 1
	v_add_f32_dpp v41, v41, v41 row_bcast:31 row_mask:0xc bank_mask:0xf
	s_nop 1
	v_readlane_b32 s98, v41, 63
	s_nop 1
	v_mov_b32_e32 v41, s98
	v_fmamk_f32 v41, v41, 0x3a800000, v206
	v_cmp_gt_f32_e32 vcc, s16, v41
	v_mul_f32_e32 v47, 0x4b800000, v41
	s_nop 0
	v_cndmask_b32_e32 v41, v41, v47, vcc
	v_rsq_f32_e32 v41, v41
	s_nop 0
	v_mul_f32_e32 v47, 0x45800000, v41
	v_cndmask_b32_e32 v58, v41, v47, vcc
	v_pk_mul_f32 v[32:33], v[32:33], v[58:59] op_sel_hi:[1,0]
	v_pk_mul_f32 v[34:35], v[34:35], v[58:59] op_sel_hi:[1,0]
	v_pk_fma_f32 v[32:33], v[84:85], v[32:33], v[54:55]
	v_pk_fma_f32 v[34:35], v[64:65], v[34:35], v[56:57]
	v_cvt_pk_bf16_f32 v32, v32, v33
	v_cvt_pk_bf16_f32 v33, v34, v35
	v_pk_mul_f32 v[34:35], v[36:37], v[58:59] op_sel_hi:[1,0]
	v_pk_mul_f32 v[36:37], v[38:39], v[58:59] op_sel_hi:[1,0]
	v_pk_fma_f32 v[34:35], v[62:63], v[34:35], v[50:51]
	v_pk_fma_f32 v[36:37], v[60:61], v[36:37], v[52:53]
	v_cvt_pk_bf16_f32 v34, v34, v35
	v_cvt_pk_bf16_f32 v35, v36, v37
	v_pk_mul_f32 v[36:37], v[96:97], v[58:59] op_sel_hi:[1,0]
	v_pk_mul_f32 v[38:39], v[92:93], v[58:59] op_sel_hi:[1,0]
	v_pk_fma_f32 v[36:37], v[36:37], v[98:99], v[76:77]
	v_pk_fma_f32 v[38:39], v[38:39], v[94:95], v[78:79]
	v_cvt_pk_bf16_f32 v36, v36, v37
	v_cvt_pk_bf16_f32 v37, v38, v39
	v_pk_mul_f32 v[38:39], v[90:91], v[58:59] op_sel_hi:[1,0]
	v_pk_mul_f32 v[50:51], v[88:89], v[58:59] op_sel_hi:[1,0]
	v_pk_add_f32 v[52:53], v[82:83], 1.0 op_sel_hi:[1,0]
	v_cmp_lt_i32_e32 vcc, s50, v40
	v_pk_fma_f32 v[38:39], v[38:39], v[80:81], v[72:73]
	v_pk_fma_f32 v[50:51], v[50:51], v[52:53], v[74:75]
	s_or_b64 s[10:11], vcc, s[10:11]
	v_cvt_pk_bf16_f32 v38, v38, v39
	v_cvt_pk_bf16_f32 v39, v50, v51
	global_store_dwordx4 v[48:49], v[32:35], off
	global_store_dwordx4 v[48:49], v[36:39], off offset:1024
	s_andn2_b64 exec, exec, s[10:11]
	s_cbranch_execnz .LBB0_1410

; __device__ __forceinline__ void rowpass(const Params& p, int mode, const float* __restrict__ lg, const float* __restrict__ lb,
;                         const float* __restrict__ modl, int shoff, int scoff) {
;     ...
; #pragma unroll
;       for (int i = 0; i < 2; ++i) {
;         const u32x4 w = *(const u32x4*)(xr + i * 512 + lane * 8);
;         v[2 * i].x = __uint_as_float(w.x << 16); v[2 * i].y = __uint_as_float(w.x & 0xffff0000u);
;         v[2 * i].z = __uint_as_float(w.y << 16); v[2 * i].w = __uint_as_float(w.y & 0xffff0000u);
;         v[2 * i + 1].x = __uint_as_float(w.z << 16); v[2 * i + 1].y = __uint_as_float(w.z & 0xffff0000u);
;         v[2 * i + 1].z = __uint_as_float(w.w << 16); v[2 * i + 1].w = __uint_as_float(w.w & 0xffff0000u);
;       }
;     }
;     if (mode & 1) {
;       float s = 0.f;
; #pragma unroll
;       for (int i = 0; i < 4; ++i) s += v[i].x + v[i].y + v[i].z + v[i].w;
;       const float mu = wave_sum(s) * (1.f / D);
;       float q = 0.f;
; #pragma unroll
;       for (int i = 0; i < 4; ++i) {
;         v[i].x -= mu; v[i].y -= mu; v[i].z -= mu; v[i].w -= mu;
;         q += v[i].x * v[i].x + v[i].y * v[i].y + v[i].z * v[i].z + v[i].w * v[i].w;
;       }
;       const float rstd = rsqrtf(wave_sum(q) * (1.f / D) + LN_EPS);
; #pragma unroll
;       for (int k = 0; k < 4; ++k) {
;         const int c = CK(k);
;         const float4 g = *(const float4*)(lg + c), be = *(const float4*)(lb + c);
;         v[k].x = v[k].x * rstd * g.x + be.x; v[k].y = v[k].y * rstd * g.y + be.y;
;         v[k].z = v[k].z * rstd * g.z + be.z; v[k].w = v[k].w * rstd * g.w + be.w;
;         if ((mode & 2) && n >= CTXL) *(float4*)(p.out + ((size_t)b * SEQ + (n - CTXL)) * D + c) = v[k];
.LBB0_1422:
	v_ashrrev_i32_e32 v1, 31, v0
	v_lshlrev_b64 v[10:11], 11, v[0:1]
	v_lshl_add_u64 v[14:15], v[6:7], 0, v[10:11]
	global_load_dwordx4 v[10:13], v[14:15], off
	s_nop 0
	global_load_dwordx4 v[14:17], v[14:15], off offset:1024
	s_waitcnt vmcnt(1)
	v_lshlrev_b32_e32 v18, 16, v10
	v_and_b32_e32 v19, 0xffff0000, v10
	v_lshlrev_b32_e32 v22, 16, v12
	v_and_b32_e32 v23, 0xffff0000, v12
	v_lshlrev_b32_e32 v10, 16, v11
	v_lshlrev_b32_e32 v12, 16, v13
	s_waitcnt vmcnt(0)
	v_lshlrev_b32_e32 v38, 16, v16
	v_and_b32_e32 v39, 0xffff0000, v16
	v_lshlrev_b32_e32 v40, 16, v17
	v_and_b32_e32 v41, 0xffff0000, v17
	v_mov_b32_e32 v16, v22
	v_mov_b32_e32 v17, v18
	v_mov_b32_e32 v24, v23
	v_mov_b32_e32 v25, v19
	v_and_b32_e32 v11, 0xffff0000, v11
	v_and_b32_e32 v13, 0xffff0000, v13
	v_lshlrev_b32_e32 v36, 16, v14
	v_and_b32_e32 v37, 0xffff0000, v14
	v_mov_b32_e32 v26, v12
	v_mov_b32_e32 v27, v10
	v_pk_add_f32 v[16:17], v[16:17], v[24:25]
	v_lshlrev_b32_e32 v14, 16, v15
	v_mov_b32_e32 v28, v13
	v_mov_b32_e32 v29, v11
	v_mov_b32_e32 v42, v38
	v_mov_b32_e32 v43, v36
	v_mov_b32_e32 v44, v39
	v_mov_b32_e32 v45, v37
	v_pk_add_f32 v[16:17], v[16:17], v[26:27]
	v_and_b32_e32 v15, 0xffff0000, v15
	v_mov_b32_e32 v46, v40
	v_mov_b32_e32 v47, v14
	v_pk_add_f32 v[24:25], v[42:43], v[44:45]
	v_pk_add_f32 v[16:17], v[16:17], v[28:29]
	v_mov_b32_e32 v48, v41
	v_mov_b32_e32 v49, v15
	v_pk_add_f32 v[24:25], v[24:25], v[46:47]
	v_add_f32_e32 v1, 0, v17
	v_pk_add_f32 v[24:25], v[24:25], v[48:49]
	v_add_f32_e32 v1, v16, v1
	v_add_f32_e32 v1, v25, v1
	v_add_f32_e32 v1, v24, v1
	s_waitcnt lgkmcnt(0)
	s_waitcnt lgkmcnt(0)
	s_nop 1
	v_add_f32_dpp v1, v1, v1 quad_perm:[1,0,3,2] row_mask:0xf bank_mask:0xf
	s_nop 1
	v_add_f32_dpp v1, v1, v1 quad_perm:[2,3,0,1] row_mask:0xf bank_mask:0xf
	s_nop 1
	v_add_f32_dpp v1, v1, v1 row_half_mirror row_mask:0xf bank_mask:0xf
	s_nop 1
	v_add_f32_dpp v1, v1, v1 row_mirror row_mask:0xf bank_mask:0xf
	s_nop 1
	v_add_f32_dpp v1, v1, v1 row_bcast:15 row_mask:0xa bank_mask:0xf
	s_nop 1
	v_add_f32_dpp v1, v1, v1 row_bcast:31 row_mask:0xc bank_mask:0xf
	s_nop 1
	v_readlane_b32 s98, v1, 63
	s_nop 1
	v_mov_b32_e32 v1, s98
	v_mul_f32_e32 v20, 0x3a800000, v1
	v_pk_add_f32 v[28:29], v[18:19], v[20:21] op_sel_hi:[1,0] neg_lo:[0,1] neg_hi:[0,1]
	v_pk_add_f32 v[24:25], v[22:23], v[20:21] op_sel_hi:[1,0] neg_lo:[0,1] neg_hi:[0,1]
	v_pk_add_f32 v[26:27], v[10:11], v[20:21] op_sel_hi:[1,0] neg_lo:[0,1] neg_hi:[0,1]
	v_pk_add_f32 v[22:23], v[12:13], v[20:21] op_sel_hi:[1,0] neg_lo:[0,1] neg_hi:[0,1]
	v_pk_add_f32 v[16:17], v[36:37], v[20:21] op_sel_hi:[1,0] neg_lo:[0,1] neg_hi:[0,1]
	v_pk_add_f32 v[12:13], v[38:39], v[20:21] op_sel_hi:[1,0] neg_lo:[0,1] neg_hi:[0,1]
	v_pk_mul_f32 v[18:19], v[28:29], v[28:29]
	v_pk_mul_f32 v[38:39], v[24:25], v[24:25]
	v_pk_add_f32 v[14:15], v[14:15], v[20:21] op_sel_hi:[1,0] neg_lo:[0,1] neg_hi:[0,1]
	v_pk_add_f32 v[10:11], v[40:41], v[20:21] op_sel_hi:[1,0] neg_lo:[0,1] neg_hi:[0,1]
	v_pk_mul_f32 v[36:37], v[26:27], v[26:27]
	v_pk_mul_f32 v[40:41], v[22:23], v[22:23]
	v_pk_mul_f32 v[42:43], v[16:17], v[16:17]
	v_add_f32_e32 v1, v38, v39
	v_add_f32_e32 v9, v18, v19
	v_pk_mul_f32 v[44:45], v[14:15], v[14:15]
	v_pk_mul_f32 v[46:47], v[12:13], v[12:13]
	v_add_f32_e32 v18, v42, v43
	v_add_f32_e32 v1, v40, v1
	v_add_f32_e32 v9, v36, v9
	v_pk_mul_f32 v[48:49], v[10:11], v[10:11]
	v_add_f32_e32 v19, v46, v47
	v_add_f32_e32 v18, v44, v18
	v_add_f32_e32 v1, v41, v1
	v_add_f32_e32 v9, v37, v9
	v_add_f32_e32 v19, v48, v19
	v_add_f32_e32 v18, v45, v18
	v_add_f32_e32 v1, v9, v1
	v_add_f32_e32 v1, v18, v1
	v_add_f32_e32 v9, v49, v19
	v_add_f32_e32 v1, v9, v1
	ds_bpermute_b32 v9, v21, v1
	v_mul_hi_i32 v18, v0, s43
	v_lshrrev_b32_e32 v19, 31, v18
	v_ashrrev_i32_e32 v18, 11, v18
	v_add_u32_e32 v18, v18, v19
	s_waitcnt lgkmcnt(0)
	v_add_f32_e32 v1, v1, v9
	ds_bpermute_b32 v9, v30, v1
	v_mul_i32_i24_e32 v19, 0x1100, v18
	v_sub_u32_e32 v19, v0, v19
	v_cmp_lt_i32_e32 vcc, s2, v19
	s_waitcnt lgkmcnt(0)
	v_add_f32_e32 v1, v1, v9
	ds_bpermute_b32 v9, v31, v1
	s_waitcnt lgkmcnt(0)
	v_add_f32_e32 v1, v1, v9
	ds_bpermute_b32 v9, v32, v1
	s_waitcnt lgkmcnt(0)
	v_add_f32_e32 v1, v1, v9
	ds_bpermute_b32 v9, v33, v1
	s_waitcnt lgkmcnt(0)
	v_add_f32_e32 v1, v1, v9
	ds_bpermute_b32 v9, v34, v1
	s_and_saveexec_b64 s[10:11], vcc
	s_cbranch_execz .LBB0_1421
	v_add_u32_e32 v160, 0xffffff00, v19
	v_ashrrev_i32_e32 v19, 31, v18
	v_lshlrev_b64 v[18:19], 24, v[18:19]
	v_lshlrev_b64 v[36:37], 12, v[160:161]
	v_lshl_add_u64 v[18:19], s[88:89], 0, v[18:19]
	v_lshl_add_u64 v[18:19], v[18:19], 0, v[36:37]
	global_load_dwordx4 v[36:39], v[4:5], off offset:16
	global_load_dwordx4 v[40:43], v[4:5], off
	global_load_dwordx4 v[44:47], v[2:3], off offset:16
	global_load_dwordx4 v[48:51], v[2:3], off
	s_waitcnt lgkmcnt(0)
	v_add_f32_e32 v1, v1, v9
	v_fmamk_f32 v1, v1, 0x3a800000, v206
	v_cmp_gt_f32_e32 vcc, s82, v1
	v_mul_f32_e32 v9, 0x4b800000, v1
	s_nop 0
	v_cndmask_b32_e32 v1, v1, v9, vcc
	v_rsq_f32_e32 v1, v1
	s_nop 0
	v_mul_f32_e32 v9, 0x45800000, v1
	v_cndmask_b32_e32 v20, v1, v9, vcc
	v_mov_b32_e32 v9, v161
	v_pk_mul_f32 v[28:29], v[28:29], v[20:21] op_sel_hi:[1,0]
	v_pk_mul_f32 v[26:27], v[26:27], v[20:21] op_sel_hi:[1,0]
	v_pk_mul_f32 v[24:25], v[24:25], v[20:21] op_sel_hi:[1,0]
	v_pk_mul_f32 v[22:23], v[22:23], v[20:21] op_sel_hi:[1,0]
	v_lshl_add_u64 v[18:19], v[18:19], 0, v[8:9]
	v_pk_mul_f32 v[16:17], v[16:17], v[20:21] op_sel_hi:[1,0]
	v_pk_mul_f32 v[14:15], v[14:15], v[20:21] op_sel_hi:[1,0]
	v_pk_mul_f32 v[12:13], v[12:13], v[20:21] op_sel_hi:[1,0]
	v_pk_mul_f32 v[10:11], v[10:11], v[20:21] op_sel_hi:[1,0]
	s_waitcnt vmcnt(1)
	v_pk_fma_f32 v[24:25], v[24:25], v[44:45], v[36:37]
	s_waitcnt vmcnt(0)
	v_pk_fma_f32 v[40:41], v[28:29], v[48:49], v[40:41]
	v_pk_fma_f32 v[42:43], v[26:27], v[50:51], v[42:43]
	v_pk_fma_f32 v[26:27], v[22:23], v[46:47], v[38:39]
	global_store_dwordx4 v[18:19], v[40:43], off
	global_store_dwordx4 v[18:19], v[24:27], off offset:16
	global_load_dwordx4 v[22:25], v[4:5], off offset:2064
	s_nop 0
	global_load_dwordx4 v[26:29], v[4:5], off offset:2048
	global_load_dwordx4 v[36:39], v[2:3], off offset:2064
	global_load_dwordx4 v[40:43], v[2:3], off offset:2048
	s_waitcnt vmcnt(1)
	v_pk_fma_f32 v[12:13], v[12:13], v[36:37], v[22:23]
	s_waitcnt vmcnt(0)
	v_pk_fma_f32 v[26:27], v[16:17], v[40:41], v[26:27]
	v_pk_fma_f32 v[28:29], v[14:15], v[42:43], v[28:29]
	v_pk_fma_f32 v[14:15], v[10:11], v[38:39], v[24:25]
	global_store_dwordx4 v[18:19], v[26:29], off offset:2048
	global_store_dwordx4 v[18:19], v[12:15], off offset:2064
	s_branch .LBB0_1421

; DI int otid() { int t = threadIdx.x; asm volatile("" : "+v"(t)); return t; }
; __global__ void __launch_bounds__(512, 2) fwd_megakernel(Params p) {
;   cg::grid_group grid = cg::this_grid();
;   __shared__ __attribute__((aligned(16))) char smem[LDS_BYTES];
;   __shared__ int s_item;
;   const int tid = otid();
	.amdhsa_kernel _Z14fwd_megakernel6Params
		.amdhsa_group_segment_fixed_size 140292
		.amdhsa_private_segment_fixed_size 0
		.amdhsa_kernarg_size 528
		.amdhsa_user_sgpr_count 2
		.amdhsa_user_sgpr_dispatch_ptr 0
		.amdhsa_user_sgpr_queue_ptr 0
		.amdhsa_user_sgpr_kernarg_segment_ptr 1
		.amdhsa_user_sgpr_dispatch_id 0
		.amdhsa_user_sgpr_kernarg_preload_length 0
		.amdhsa_user_sgpr_kernarg_preload_offset 0
		.amdhsa_user_sgpr_private_segment_size 0
		.amdhsa_uses_dynamic_stack 0
		.amdhsa_enable_private_segment 0
		.amdhsa_system_sgpr_workgroup_id_x 1
		.amdhsa_system_sgpr_workgroup_id_y 0
		.amdhsa_system_sgpr_workgroup_id_z 0
		.amdhsa_system_sgpr_workgroup_info 0
		.amdhsa_system_vgpr_workitem_id 2
		.amdhsa_next_free_vgpr 256
		.amdhsa_next_free_sgpr 102
		.amdhsa_accum_offset 256
		.amdhsa_reserve_vcc 1
		.amdhsa_float_round_mode_32 0
		.amdhsa_float_round_mode_16_64 0
		.amdhsa_float_denorm_mode_32 3
		.amdhsa_float_denorm_mode_16_64 3
		.amdhsa_dx10_clamp 1
		.amdhsa_ieee_mode 1
		.amdhsa_fp16_overflow 0
		.amdhsa_tg_split 0
		.amdhsa_exception_fp_ieee_invalid_op 0
		.amdhsa_exception_fp_denorm_src 0
		.amdhsa_exception_fp_ieee_div_zero 0
		.amdhsa_exception_fp_ieee_overflow 0
		.amdhsa_exception_fp_ieee_underflow 0
		.amdhsa_exception_fp_ieee_inexact 0
		.amdhsa_exception_int_div_zero 0
	.end_amdhsa_kernel

; DI int otid() { int t = threadIdx.x; asm volatile("" : "+v"(t)); return t; }
; __global__ void __launch_bounds__(512, 2) fwd_megakernel(Params p) {
;   cg::grid_group grid = cg::this_grid();
;   __shared__ __attribute__((aligned(16))) char smem[LDS_BYTES];
;   __shared__ int s_item;
;   const int tid = otid();
amdhsa.kernels:
  - .agpr_count:     0
    .args:
      - .offset:         0
        .size:           272
        .value_kind:     by_value
      - .offset:         272
        .size:           4
        .value_kind:     hidden_block_count_x
      - .offset:         276
        .size:           4
        .value_kind:     hidden_block_count_y
      - .offset:         280
        .size:           4
        .value_kind:     hidden_block_count_z
      - .offset:         284
        .size:           2
        .value_kind:     hidden_group_size_x
      - .offset:         286
        .size:           2
        .value_kind:     hidden_group_size_y
      - .offset:         288
        .size:           2
        .value_kind:     hidden_group_size_z
      - .offset:         290
        .size:           2
        .value_kind:     hidden_remainder_x
      - .offset:         292
        .size:           2
        .value_kind:     hidden_remainder_y
      - .offset:         294
        .size:           2
        .value_kind:     hidden_remainder_z
      - .offset:         312
        .size:           8
        .value_kind:     hidden_global_offset_x
      - .offset:         320
        .size:           8
        .value_kind:     hidden_global_offset_y
      - .offset:         328
        .size:           8
        .value_kind:     hidden_global_offset_z
      - .offset:         336
        .size:           2
        .value_kind:     hidden_grid_dims
      - .offset:         360
        .size:           8
        .value_kind:     hidden_multigrid_sync_arg
    .group_segment_fixed_size: 140292
    .kernarg_segment_align: 8
    .kernarg_segment_size: 528
    .language:       OpenCL C
    .language_version:
      - 2
      - 0
    .max_flat_workgroup_size: 512
    .name:           _Z14fwd_megakernel6Params
    .private_segment_fixed_size: 0
    .sgpr_count:     108
    .sgpr_spill_count: 235
    .symbol:         _Z14fwd_megakernel6Params.kd
    .uniform_work_group_size: 1
    .uses_dynamic_stack: false
    .vgpr_count:     256
    .vgpr_spill_count: 0
    .wavefront_size: 64
